# cand G + the compiler's duplicate s_waitcnt lgkmcnt(0) after barrier+setprio (already waited by the inline-asm wait before the barrier) removed in the 28 mainloop hand-offs
# baseline (speedup 1.0000x reference)
.LBB0_341:
	ds_read_b128 v[152:155], v139
	ds_read_b128 v[156:159], v139 offset:1024
	ds_read_b128 v[160:163], v139 offset:2048
	ds_read_b128 v[174:177], v139 offset:3072
	ds_read_b128 v[182:185], v168
	ds_read_b128 v[186:189], v168 offset:1024
	ds_read_b128 v[190:193], v168 offset:2048
	ds_read_b128 v[194:197], v168 offset:3072
	s_add_u32 s26, s24, 0xfffc0080
	s_addc_u32 s27, s25, -1
	s_cmp_eq_u32 s64, 12
	s_cselect_b32 s29, s1, s27
	s_cselect_b32 s28, s5, s26
	s_cselect_b32 s27, s17, s31
	s_cselect_b32 s26, s19, s30
	v_lshl_add_u64 v[164:165], s[24:25], 0, v[144:145]
	s_add_i32 m0, s47, 0xc000
	ds_read_b128 v[198:201], v169
	ds_read_b128 v[202:205], v169 offset:1024
	ds_read_b128 v[206:209], v169 offset:2048
	ds_read_b128 v[210:213], v169 offset:3072
	ds_read_b128 v[214:217], v169 offset:4096
	ds_read_b128 v[218:221], v169 offset:5120
	ds_read_b128 v[222:225], v169 offset:6144
	ds_read_b128 v[226:229], v169 offset:7168
	global_load_lds_dwordx4 v[164:165], off
	v_lshl_add_u64 v[164:165], s[24:25], 0, v[146:147]
	s_add_i32 m0, s47, 0xe000
	s_nop 0
	global_load_lds_dwordx4 v[164:165], off
	s_waitcnt vmcnt(8)
	s_waitcnt lgkmcnt(0)
	s_barrier
	s_setprio 1
	v_mfma_f32_16x16x32_bf16 v[124:127], v[152:155], v[198:201], v[124:127]
	v_mfma_f32_16x16x32_bf16 v[120:123], v[160:163], v[198:201], v[120:123]
	v_mfma_f32_16x16x32_bf16 v[108:111], v[152:155], v[206:209], v[108:111]
	v_mfma_f32_16x16x32_bf16 v[104:107], v[160:163], v[206:209], v[104:107]
	v_mfma_f32_16x16x32_bf16 v[92:95], v[152:155], v[214:217], v[92:95]
	v_mfma_f32_16x16x32_bf16 v[88:91], v[160:163], v[214:217], v[88:91]
	v_mfma_f32_16x16x32_bf16 v[76:79], v[152:155], v[222:225], v[76:79]
	v_mfma_f32_16x16x32_bf16 v[72:75], v[160:163], v[222:225], v[72:75]
	v_mfma_f32_16x16x32_bf16 v[124:127], v[156:159], v[202:205], v[124:127]
	v_mfma_f32_16x16x32_bf16 v[120:123], v[174:177], v[202:205], v[120:123]
	v_mfma_f32_16x16x32_bf16 v[108:111], v[156:159], v[210:213], v[108:111]
	v_mfma_f32_16x16x32_bf16 v[104:107], v[174:177], v[210:213], v[104:107]
	v_mfma_f32_16x16x32_bf16 v[92:95], v[156:159], v[218:221], v[92:95]
	v_mfma_f32_16x16x32_bf16 v[88:91], v[174:177], v[218:221], v[88:91]
	v_mfma_f32_16x16x32_bf16 v[76:79], v[156:159], v[226:229], v[76:79]
	v_mfma_f32_16x16x32_bf16 v[72:75], v[174:177], v[226:229], v[72:75]
	v_mfma_f32_16x16x32_bf16 v[116:119], v[182:185], v[198:201], v[116:119]
	v_mfma_f32_16x16x32_bf16 v[112:115], v[190:193], v[198:201], v[112:115]
	v_mfma_f32_16x16x32_bf16 v[100:103], v[182:185], v[206:209], v[100:103]
	v_mfma_f32_16x16x32_bf16 v[96:99], v[190:193], v[206:209], v[96:99]
	v_mfma_f32_16x16x32_bf16 v[84:87], v[182:185], v[214:217], v[84:87]
	v_mfma_f32_16x16x32_bf16 v[80:83], v[190:193], v[214:217], v[80:83]
	v_mfma_f32_16x16x32_bf16 v[68:71], v[182:185], v[222:225], v[68:71]
	v_mfma_f32_16x16x32_bf16 v[64:67], v[190:193], v[222:225], v[64:67]
	v_mfma_f32_16x16x32_bf16 v[116:119], v[186:189], v[202:205], v[116:119]
	v_mfma_f32_16x16x32_bf16 v[112:115], v[194:197], v[202:205], v[112:115]
	v_mfma_f32_16x16x32_bf16 v[100:103], v[186:189], v[210:213], v[100:103]
	v_mfma_f32_16x16x32_bf16 v[96:99], v[194:197], v[210:213], v[96:99]
	v_mfma_f32_16x16x32_bf16 v[84:87], v[186:189], v[218:221], v[84:87]
	v_mfma_f32_16x16x32_bf16 v[80:83], v[194:197], v[218:221], v[80:83]
	v_mfma_f32_16x16x32_bf16 v[68:71], v[186:189], v[226:229], v[68:71]
	v_mfma_f32_16x16x32_bf16 v[64:67], v[194:197], v[226:229], v[64:67]
	s_setprio 0
	s_barrier
	s_mov_b32 m0, s43
	v_lshl_add_u64 v[164:165], s[26:27], 0, v[130:131]
	s_add_u32 s66, s26, 0x40000
	ds_read_b128 v[198:201], v169 offset:16384
	ds_read_b128 v[202:205], v169 offset:17408
	ds_read_b128 v[206:209], v169 offset:18432
	ds_read_b128 v[210:213], v169 offset:19456
	ds_read_b128 v[214:217], v169 offset:20480
	ds_read_b128 v[218:221], v169 offset:21504
	ds_read_b128 v[222:225], v169 offset:22528
	ds_read_b128 v[226:229], v169 offset:23552
	global_load_lds_dwordx4 v[164:165], off
	v_lshl_add_u64 v[178:179], s[26:27], 0, v[134:135]
	s_mov_b32 m0, s44
	s_addc_u32 s67, s27, 0
	global_load_lds_dwordx4 v[178:179], off
	v_lshl_add_u64 v[230:231], s[66:67], 0, v[130:131]
	s_mov_b32 m0, s45
	v_lshl_add_u64 v[232:233], s[28:29], 0, v[132:133]
	global_load_lds_dwordx4 v[230:231], off
	v_lshl_add_u64 v[230:231], s[66:67], 0, v[134:135]
	s_mov_b32 m0, s46
	s_nop 0
	global_load_lds_dwordx4 v[230:231], off
	v_lshl_add_u64 v[230:231], s[28:29], 0, v[128:129]
	s_mov_b32 m0, s47
	s_nop 0
	global_load_lds_dwordx4 v[230:231], off
	s_mov_b32 m0, s48
	s_nop 0
	global_load_lds_dwordx4 v[232:233], off
	s_waitcnt vmcnt(8)
	s_waitcnt lgkmcnt(0)
	s_barrier
	s_setprio 1
	v_mfma_f32_16x16x32_bf16 v[60:63], v[152:155], v[198:201], v[60:63]
	v_mfma_f32_16x16x32_bf16 v[56:59], v[160:163], v[198:201], v[56:59]
	v_mfma_f32_16x16x32_bf16 v[44:47], v[152:155], v[206:209], v[44:47]
	v_mfma_f32_16x16x32_bf16 v[40:43], v[160:163], v[206:209], v[40:43]
	v_mfma_f32_16x16x32_bf16 v[28:31], v[152:155], v[214:217], v[28:31]
	v_mfma_f32_16x16x32_bf16 v[24:27], v[160:163], v[214:217], v[24:27]
	v_mfma_f32_16x16x32_bf16 v[12:15], v[152:155], v[222:225], v[12:15]
	v_mfma_f32_16x16x32_bf16 v[8:11], v[160:163], v[222:225], v[8:11]
	v_mfma_f32_16x16x32_bf16 v[60:63], v[156:159], v[202:205], v[60:63]
	v_mfma_f32_16x16x32_bf16 v[56:59], v[174:177], v[202:205], v[56:59]
	v_mfma_f32_16x16x32_bf16 v[44:47], v[156:159], v[210:213], v[44:47]
	v_mfma_f32_16x16x32_bf16 v[40:43], v[174:177], v[210:213], v[40:43]
	v_mfma_f32_16x16x32_bf16 v[28:31], v[156:159], v[218:221], v[28:31]
	v_mfma_f32_16x16x32_bf16 v[24:27], v[174:177], v[218:221], v[24:27]
	v_mfma_f32_16x16x32_bf16 v[12:15], v[156:159], v[226:229], v[12:15]
	v_mfma_f32_16x16x32_bf16 v[8:11], v[174:177], v[226:229], v[8:11]
	v_mfma_f32_16x16x32_bf16 v[52:55], v[182:185], v[198:201], v[52:55]
	v_mfma_f32_16x16x32_bf16 v[48:51], v[190:193], v[198:201], v[48:51]
	v_mfma_f32_16x16x32_bf16 v[36:39], v[182:185], v[206:209], v[36:39]
	v_mfma_f32_16x16x32_bf16 v[32:35], v[190:193], v[206:209], v[32:35]
	v_mfma_f32_16x16x32_bf16 v[20:23], v[182:185], v[214:217], v[20:23]
	v_mfma_f32_16x16x32_bf16 v[16:19], v[190:193], v[214:217], v[16:19]
	v_mfma_f32_16x16x32_bf16 v[4:7], v[182:185], v[222:225], v[4:7]
	v_mfma_f32_16x16x32_bf16 v[0:3], v[190:193], v[222:225], v[0:3]
	v_mfma_f32_16x16x32_bf16 v[52:55], v[186:189], v[202:205], v[52:55]
	v_mfma_f32_16x16x32_bf16 v[48:51], v[194:197], v[202:205], v[48:51]
	v_mfma_f32_16x16x32_bf16 v[36:39], v[186:189], v[210:213], v[36:39]
	v_mfma_f32_16x16x32_bf16 v[32:35], v[194:197], v[210:213], v[32:35]
	v_mfma_f32_16x16x32_bf16 v[20:23], v[186:189], v[218:221], v[20:23]
	v_mfma_f32_16x16x32_bf16 v[16:19], v[194:197], v[218:221], v[16:19]
	v_mfma_f32_16x16x32_bf16 v[4:7], v[186:189], v[226:229], v[4:7]
	v_mfma_f32_16x16x32_bf16 v[0:3], v[194:197], v[226:229], v[0:3]
	s_setprio 0
	s_barrier
	ds_read_b128 v[152:155], v170
	ds_read_b128 v[156:159], v170 offset:1024
	ds_read_b128 v[160:163], v170 offset:2048
	ds_read_b128 v[174:177], v170 offset:3072
	ds_read_b128 v[182:185], v171
	ds_read_b128 v[186:189], v171 offset:1024
	ds_read_b128 v[190:193], v171 offset:2048
	ds_read_b128 v[194:197], v171 offset:3072
	s_add_u32 s28, s28, 0x40000
	s_addc_u32 s29, s29, 0
	s_mov_b32 m0, s49
	v_lshl_add_u64 v[234:235], s[28:29], 0, v[128:129]
	ds_read_b128 v[198:201], v169 offset:32768
	ds_read_b128 v[202:205], v169 offset:33792
	ds_read_b128 v[206:209], v169 offset:34816
	ds_read_b128 v[210:213], v169 offset:35840
	ds_read_b128 v[214:217], v169 offset:36864
	ds_read_b128 v[218:221], v169 offset:37888
	ds_read_b128 v[222:225], v169 offset:38912
	ds_read_b128 v[226:229], v169 offset:39936
	global_load_lds_dwordx4 v[234:235], off
	v_lshl_add_u64 v[234:235], s[28:29], 0, v[132:133]
	s_mov_b32 m0, s50
	s_nop 0
	global_load_lds_dwordx4 v[234:235], off
	s_waitcnt vmcnt(8)
	s_waitcnt lgkmcnt(0)
	s_barrier
	s_setprio 1
	v_mfma_f32_16x16x32_bf16 v[124:127], v[152:155], v[198:201], v[124:127]
	v_mfma_f32_16x16x32_bf16 v[120:123], v[160:163], v[198:201], v[120:123]
	v_mfma_f32_16x16x32_bf16 v[108:111], v[152:155], v[206:209], v[108:111]
	v_mfma_f32_16x16x32_bf16 v[104:107], v[160:163], v[206:209], v[104:107]
	v_mfma_f32_16x16x32_bf16 v[92:95], v[152:155], v[214:217], v[92:95]
	v_mfma_f32_16x16x32_bf16 v[88:91], v[160:163], v[214:217], v[88:91]
	v_mfma_f32_16x16x32_bf16 v[76:79], v[152:155], v[222:225], v[76:79]
	v_mfma_f32_16x16x32_bf16 v[72:75], v[160:163], v[222:225], v[72:75]
	v_mfma_f32_16x16x32_bf16 v[124:127], v[156:159], v[202:205], v[124:127]
	v_mfma_f32_16x16x32_bf16 v[120:123], v[174:177], v[202:205], v[120:123]
	v_mfma_f32_16x16x32_bf16 v[108:111], v[156:159], v[210:213], v[108:111]
	v_mfma_f32_16x16x32_bf16 v[104:107], v[174:177], v[210:213], v[104:107]
	v_mfma_f32_16x16x32_bf16 v[92:95], v[156:159], v[218:221], v[92:95]
	v_mfma_f32_16x16x32_bf16 v[88:91], v[174:177], v[218:221], v[88:91]
	v_mfma_f32_16x16x32_bf16 v[76:79], v[156:159], v[226:229], v[76:79]
	v_mfma_f32_16x16x32_bf16 v[72:75], v[174:177], v[226:229], v[72:75]
	v_mfma_f32_16x16x32_bf16 v[116:119], v[182:185], v[198:201], v[116:119]
	v_mfma_f32_16x16x32_bf16 v[112:115], v[190:193], v[198:201], v[112:115]
	v_mfma_f32_16x16x32_bf16 v[100:103], v[182:185], v[206:209], v[100:103]
	v_mfma_f32_16x16x32_bf16 v[96:99], v[190:193], v[206:209], v[96:99]
	v_mfma_f32_16x16x32_bf16 v[84:87], v[182:185], v[214:217], v[84:87]
	v_mfma_f32_16x16x32_bf16 v[80:83], v[190:193], v[214:217], v[80:83]
	v_mfma_f32_16x16x32_bf16 v[68:71], v[182:185], v[222:225], v[68:71]
	v_mfma_f32_16x16x32_bf16 v[64:67], v[190:193], v[222:225], v[64:67]
	v_mfma_f32_16x16x32_bf16 v[116:119], v[186:189], v[202:205], v[116:119]
	v_mfma_f32_16x16x32_bf16 v[112:115], v[194:197], v[202:205], v[112:115]
	v_mfma_f32_16x16x32_bf16 v[100:103], v[186:189], v[210:213], v[100:103]
	v_mfma_f32_16x16x32_bf16 v[96:99], v[194:197], v[210:213], v[96:99]
	v_mfma_f32_16x16x32_bf16 v[84:87], v[186:189], v[218:221], v[84:87]
	v_mfma_f32_16x16x32_bf16 v[80:83], v[194:197], v[218:221], v[80:83]
	v_mfma_f32_16x16x32_bf16 v[68:71], v[186:189], v[226:229], v[68:71]
	v_mfma_f32_16x16x32_bf16 v[64:67], v[194:197], v[226:229], v[64:67]
	s_setprio 0
	s_barrier
	s_mov_b32 m0, s54
	v_lshl_add_u64 v[164:165], v[164:165], 0, s[12:13]
	s_add_u32 s26, s26, 0x40080
	ds_read_b128 v[198:201], v169 offset:49152
	ds_read_b128 v[202:205], v169 offset:50176
	ds_read_b128 v[206:209], v169 offset:51200
	ds_read_b128 v[210:213], v169 offset:52224
	ds_read_b128 v[214:217], v169 offset:53248
	ds_read_b128 v[218:221], v169 offset:54272
	ds_read_b128 v[222:225], v169 offset:55296
	ds_read_b128 v[226:229], v169 offset:56320
	global_load_lds_dwordx4 v[164:165], off
	v_lshl_add_u64 v[164:165], v[178:179], 0, s[12:13]
	s_mov_b32 m0, s55
	s_addc_u32 s27, s27, 0
	global_load_lds_dwordx4 v[164:165], off
	v_lshl_add_u64 v[164:165], s[26:27], 0, v[130:131]
	s_mov_b32 m0, s58
	s_nop 0
	global_load_lds_dwordx4 v[164:165], off
	v_lshl_add_u64 v[164:165], s[26:27], 0, v[134:135]
	s_mov_b32 m0, s59
	s_nop 0
	global_load_lds_dwordx4 v[164:165], off
	v_lshl_add_u64 v[164:165], v[230:231], 0, s[12:13]
	s_mov_b32 m0, s56
	s_nop 0
	global_load_lds_dwordx4 v[164:165], off
	v_lshl_add_u64 v[164:165], v[232:233], 0, s[12:13]
	s_mov_b32 m0, s57
	s_nop 0
	global_load_lds_dwordx4 v[164:165], off
	s_waitcnt vmcnt(8)
	s_waitcnt lgkmcnt(0)
	s_barrier
	s_setprio 1
	v_mfma_f32_16x16x32_bf16 v[60:63], v[152:155], v[198:201], v[60:63]
	v_mfma_f32_16x16x32_bf16 v[56:59], v[160:163], v[198:201], v[56:59]
	v_mfma_f32_16x16x32_bf16 v[44:47], v[152:155], v[206:209], v[44:47]
	v_mfma_f32_16x16x32_bf16 v[40:43], v[160:163], v[206:209], v[40:43]
	v_mfma_f32_16x16x32_bf16 v[28:31], v[152:155], v[214:217], v[28:31]
	v_mfma_f32_16x16x32_bf16 v[24:27], v[160:163], v[214:217], v[24:27]
	v_mfma_f32_16x16x32_bf16 v[12:15], v[152:155], v[222:225], v[12:15]
	v_mfma_f32_16x16x32_bf16 v[8:11], v[160:163], v[222:225], v[8:11]
	v_mfma_f32_16x16x32_bf16 v[60:63], v[156:159], v[202:205], v[60:63]
	v_mfma_f32_16x16x32_bf16 v[56:59], v[174:177], v[202:205], v[56:59]
	v_mfma_f32_16x16x32_bf16 v[44:47], v[156:159], v[210:213], v[44:47]
	v_mfma_f32_16x16x32_bf16 v[40:43], v[174:177], v[210:213], v[40:43]
	v_mfma_f32_16x16x32_bf16 v[28:31], v[156:159], v[218:221], v[28:31]
	v_mfma_f32_16x16x32_bf16 v[24:27], v[174:177], v[218:221], v[24:27]
	v_mfma_f32_16x16x32_bf16 v[12:15], v[156:159], v[226:229], v[12:15]
	v_mfma_f32_16x16x32_bf16 v[8:11], v[174:177], v[226:229], v[8:11]
	v_mfma_f32_16x16x32_bf16 v[52:55], v[182:185], v[198:201], v[52:55]
	v_mfma_f32_16x16x32_bf16 v[48:51], v[190:193], v[198:201], v[48:51]
	v_mfma_f32_16x16x32_bf16 v[36:39], v[182:185], v[206:209], v[36:39]
	v_mfma_f32_16x16x32_bf16 v[32:35], v[190:193], v[206:209], v[32:35]
	v_mfma_f32_16x16x32_bf16 v[20:23], v[182:185], v[214:217], v[20:23]
	v_mfma_f32_16x16x32_bf16 v[16:19], v[190:193], v[214:217], v[16:19]
	v_mfma_f32_16x16x32_bf16 v[4:7], v[182:185], v[222:225], v[4:7]
	v_mfma_f32_16x16x32_bf16 v[0:3], v[190:193], v[222:225], v[0:3]
	v_mfma_f32_16x16x32_bf16 v[52:55], v[186:189], v[202:205], v[52:55]
	v_mfma_f32_16x16x32_bf16 v[48:51], v[194:197], v[202:205], v[48:51]
	v_mfma_f32_16x16x32_bf16 v[36:39], v[186:189], v[210:213], v[36:39]
	v_mfma_f32_16x16x32_bf16 v[32:35], v[194:197], v[210:213], v[32:35]
	v_mfma_f32_16x16x32_bf16 v[20:23], v[186:189], v[218:221], v[20:23]
	v_mfma_f32_16x16x32_bf16 v[16:19], v[194:197], v[218:221], v[16:19]
	v_mfma_f32_16x16x32_bf16 v[4:7], v[186:189], v[226:229], v[4:7]
	v_mfma_f32_16x16x32_bf16 v[0:3], v[194:197], v[226:229], v[0:3]
	s_setprio 0
	s_barrier
	s_add_i32 s64, s64, 2
	s_add_u32 s24, s24, 0x100
	s_addc_u32 s25, s25, 0
	s_add_u32 s30, s30, 0x100
	s_addc_u32 s31, s31, 0
	s_cmp_gt_u32 s64, 13
	s_cbranch_scc0 .LBB0_341
	s_and_b64 vcc, exec, s[14:15]
	s_cbranch_vccz .LBB0_344
	s_barrier

.LBB0_596:
	v_add_u32_e32 v178, s95, v165
	v_add_u32_e32 v200, s86, v165
	ds_read_b128 v[156:159], v178
	ds_read_b128 v[170:173], v178 offset:1024
	ds_read_b128 v[174:177], v178 offset:2048
	ds_read_b128 v[178:181], v178 offset:3072
	ds_read_b128 v[182:185], v200
	ds_read_b128 v[186:189], v200 offset:1024
	ds_read_b128 v[190:193], v200 offset:2048
	ds_read_b128 v[204:207], v200 offset:3072
	s_add_u32 s43, s44, 0xfffc0080
	s_addc_u32 s72, s45, -1
	s_cmp_eq_u32 s42, 12
	s_cselect_b32 s77, s57, s72
	s_cselect_b32 s76, s91, s43
	s_cselect_b32 vcc_hi, s1, s65
	s_cselect_b32 vcc_lo, s53, s64
	v_lshl_add_u64 v[232:233], s[44:45], 0, v[152:153]
	s_add_i32 m0, s48, 0xc000
	ds_read_b128 v[208:211], v169
	ds_read_b128 v[212:215], v169 offset:1024
	ds_read_b128 v[216:219], v169 offset:2048
	ds_read_b128 v[220:223], v169 offset:3072
	ds_read_b128 v[224:227], v169 offset:4096
	ds_read_b128 v[228:231], v169 offset:5120
	ds_read_b128 v[238:241], v169 offset:6144
	ds_read_b128 v[242:245], v169 offset:7168
	global_load_lds_dwordx4 v[232:233], off
	v_lshl_add_u64 v[232:233], s[44:45], 0, v[154:155]
	s_add_i32 m0, s48, 0xe000
	s_nop 0
	global_load_lds_dwordx4 v[232:233], off
	s_waitcnt vmcnt(8)
	s_waitcnt lgkmcnt(0)
	s_barrier
	s_setprio 1
	v_mfma_f32_16x16x32_bf16 v[142:145], v[156:159], v[208:211], v[142:145]
	v_mfma_f32_16x16x32_bf16 v[138:141], v[174:177], v[208:211], v[138:141]
	v_mfma_f32_16x16x32_bf16 v[126:129], v[156:159], v[216:219], v[126:129]
	v_mfma_f32_16x16x32_bf16 v[122:125], v[174:177], v[216:219], v[122:125]
	v_mfma_f32_16x16x32_bf16 v[110:113], v[156:159], v[224:227], v[110:113]
	v_mfma_f32_16x16x32_bf16 v[106:109], v[174:177], v[224:227], v[106:109]
	v_mfma_f32_16x16x32_bf16 v[94:97], v[156:159], v[238:241], v[94:97]
	v_mfma_f32_16x16x32_bf16 v[90:93], v[174:177], v[238:241], v[90:93]
	v_mfma_f32_16x16x32_bf16 v[142:145], v[170:173], v[212:215], v[142:145]
	v_mfma_f32_16x16x32_bf16 v[138:141], v[178:181], v[212:215], v[138:141]
	v_mfma_f32_16x16x32_bf16 v[126:129], v[170:173], v[220:223], v[126:129]
	v_mfma_f32_16x16x32_bf16 v[122:125], v[178:181], v[220:223], v[122:125]
	v_mfma_f32_16x16x32_bf16 v[110:113], v[170:173], v[228:231], v[110:113]
	v_mfma_f32_16x16x32_bf16 v[106:109], v[178:181], v[228:231], v[106:109]
	v_mfma_f32_16x16x32_bf16 v[94:97], v[170:173], v[242:245], v[94:97]
	v_mfma_f32_16x16x32_bf16 v[90:93], v[178:181], v[242:245], v[90:93]
	v_mfma_f32_16x16x32_bf16 v[134:137], v[182:185], v[208:211], v[134:137]
	v_mfma_f32_16x16x32_bf16 v[130:133], v[190:193], v[208:211], v[130:133]
	v_mfma_f32_16x16x32_bf16 v[118:121], v[182:185], v[216:219], v[118:121]
	v_mfma_f32_16x16x32_bf16 v[114:117], v[190:193], v[216:219], v[114:117]
	v_mfma_f32_16x16x32_bf16 v[102:105], v[182:185], v[224:227], v[102:105]
	v_mfma_f32_16x16x32_bf16 v[98:101], v[190:193], v[224:227], v[98:101]
	v_mfma_f32_16x16x32_bf16 v[86:89], v[182:185], v[238:241], v[86:89]
	v_mfma_f32_16x16x32_bf16 v[82:85], v[190:193], v[238:241], v[82:85]
	v_mfma_f32_16x16x32_bf16 v[134:137], v[186:189], v[212:215], v[134:137]
	v_mfma_f32_16x16x32_bf16 v[130:133], v[204:207], v[212:215], v[130:133]
	v_mfma_f32_16x16x32_bf16 v[118:121], v[186:189], v[220:223], v[118:121]
	v_mfma_f32_16x16x32_bf16 v[114:117], v[204:207], v[220:223], v[114:117]
	v_mfma_f32_16x16x32_bf16 v[102:105], v[186:189], v[228:231], v[102:105]
	v_mfma_f32_16x16x32_bf16 v[98:101], v[204:207], v[228:231], v[98:101]
	v_mfma_f32_16x16x32_bf16 v[86:89], v[186:189], v[242:245], v[86:89]
	v_mfma_f32_16x16x32_bf16 v[82:85], v[204:207], v[242:245], v[82:85]
	s_setprio 0
	s_barrier
	s_mov_b32 m0, s55
	v_lshl_add_u64 v[232:233], vcc, 0, v[0:1]
	s_add_u32 s72, vcc_lo, 0x40000
	ds_read_b128 v[208:211], v169 offset:16384
	ds_read_b128 v[212:215], v169 offset:17408
	ds_read_b128 v[216:219], v169 offset:18432
	ds_read_b128 v[220:223], v169 offset:19456
	ds_read_b128 v[224:227], v169 offset:20480
	ds_read_b128 v[228:231], v169 offset:21504
	ds_read_b128 v[238:241], v169 offset:22528
	ds_read_b128 v[242:245], v169 offset:23552
	global_load_lds_dwordx4 v[232:233], off
	v_lshl_add_u64 v[246:247], vcc, 0, v[150:151]
	s_mov_b32 m0, s85
	s_addc_u32 s73, vcc_hi, 0
	global_load_lds_dwordx4 v[246:247], off
	v_lshl_add_u64 v[248:249], s[72:73], 0, v[0:1]
	s_mov_b32 m0, s58
	v_lshl_add_u64 v[250:251], s[76:77], 0, v[148:149]
	global_load_lds_dwordx4 v[248:249], off
	v_lshl_add_u64 v[248:249], s[72:73], 0, v[150:151]
	s_mov_b32 m0, s97
	s_nop 0
	global_load_lds_dwordx4 v[248:249], off
	v_lshl_add_u64 v[248:249], s[76:77], 0, v[146:147]
	s_mov_b32 m0, s48
	s_nop 0
	global_load_lds_dwordx4 v[248:249], off
	s_mov_b32 m0, s59
	s_nop 0
	global_load_lds_dwordx4 v[250:251], off
	s_waitcnt vmcnt(8)
	s_waitcnt lgkmcnt(0)
	s_barrier
	s_setprio 1
	v_mfma_f32_16x16x32_bf16 v[78:81], v[156:159], v[208:211], v[78:81]
	v_mfma_f32_16x16x32_bf16 v[74:77], v[174:177], v[208:211], v[74:77]
	v_mfma_f32_16x16x32_bf16 v[66:69], v[156:159], v[216:219], v[66:69]
	v_mfma_f32_16x16x32_bf16 v[58:61], v[174:177], v[216:219], v[58:61]
	v_mfma_f32_16x16x32_bf16 v[46:49], v[156:159], v[224:227], v[46:49]
	v_mfma_f32_16x16x32_bf16 v[42:45], v[174:177], v[224:227], v[42:45]
	v_mfma_f32_16x16x32_bf16 v[30:33], v[156:159], v[238:241], v[30:33]
	v_mfma_f32_16x16x32_bf16 v[26:29], v[174:177], v[238:241], v[26:29]
	v_mfma_f32_16x16x32_bf16 v[78:81], v[170:173], v[212:215], v[78:81]
	v_mfma_f32_16x16x32_bf16 v[74:77], v[178:181], v[212:215], v[74:77]
	v_mfma_f32_16x16x32_bf16 v[66:69], v[170:173], v[220:223], v[66:69]
	v_mfma_f32_16x16x32_bf16 v[58:61], v[178:181], v[220:223], v[58:61]
	v_mfma_f32_16x16x32_bf16 v[46:49], v[170:173], v[228:231], v[46:49]
	v_mfma_f32_16x16x32_bf16 v[42:45], v[178:181], v[228:231], v[42:45]
	v_mfma_f32_16x16x32_bf16 v[30:33], v[170:173], v[242:245], v[30:33]
	v_mfma_f32_16x16x32_bf16 v[26:29], v[178:181], v[242:245], v[26:29]
	v_mfma_f32_16x16x32_bf16 v[70:73], v[182:185], v[208:211], v[70:73]
	v_mfma_f32_16x16x32_bf16 v[62:65], v[190:193], v[208:211], v[62:65]
	v_mfma_f32_16x16x32_bf16 v[54:57], v[182:185], v[216:219], v[54:57]
	v_mfma_f32_16x16x32_bf16 v[50:53], v[190:193], v[216:219], v[50:53]
	v_mfma_f32_16x16x32_bf16 v[38:41], v[182:185], v[224:227], v[38:41]
	v_mfma_f32_16x16x32_bf16 v[34:37], v[190:193], v[224:227], v[34:37]
	v_mfma_f32_16x16x32_bf16 v[22:25], v[182:185], v[238:241], v[22:25]
	v_mfma_f32_16x16x32_bf16 v[18:21], v[190:193], v[238:241], v[18:21]
	v_mfma_f32_16x16x32_bf16 v[70:73], v[186:189], v[212:215], v[70:73]
	v_mfma_f32_16x16x32_bf16 v[62:65], v[204:207], v[212:215], v[62:65]
	v_mfma_f32_16x16x32_bf16 v[54:57], v[186:189], v[220:223], v[54:57]
	v_mfma_f32_16x16x32_bf16 v[50:53], v[204:207], v[220:223], v[50:53]
	v_mfma_f32_16x16x32_bf16 v[38:41], v[186:189], v[228:231], v[38:41]
	v_mfma_f32_16x16x32_bf16 v[34:37], v[204:207], v[228:231], v[34:37]
	v_mfma_f32_16x16x32_bf16 v[22:25], v[186:189], v[242:245], v[22:25]
	v_mfma_f32_16x16x32_bf16 v[18:21], v[204:207], v[242:245], v[18:21]
	s_setprio 0
	s_barrier
	v_add_u32_e32 v178, s87, v165
	v_add_u32_e32 v200, s92, v165
	ds_read_b128 v[156:159], v178
	ds_read_b128 v[170:173], v178 offset:1024
	ds_read_b128 v[174:177], v178 offset:2048
	ds_read_b128 v[178:181], v178 offset:3072
	ds_read_b128 v[182:185], v200
	ds_read_b128 v[186:189], v200 offset:1024
	ds_read_b128 v[190:193], v200 offset:2048
	ds_read_b128 v[204:207], v200 offset:3072
	s_add_u32 s72, s76, 0x40000
	s_addc_u32 s73, s77, 0
	s_mov_b32 m0, s82
	v_lshl_add_u64 v[200:201], s[72:73], 0, v[146:147]
	ds_read_b128 v[208:211], v169 offset:32768
	ds_read_b128 v[212:215], v169 offset:33792
	ds_read_b128 v[216:219], v169 offset:34816
	ds_read_b128 v[220:223], v169 offset:35840
	ds_read_b128 v[224:227], v169 offset:36864
	ds_read_b128 v[228:231], v169 offset:37888
	ds_read_b128 v[238:241], v169 offset:38912
	ds_read_b128 v[242:245], v169 offset:39936
	global_load_lds_dwordx4 v[200:201], off
	v_lshl_add_u64 v[200:201], s[72:73], 0, v[148:149]
	s_mov_b32 m0, s50
	s_nop 0
	global_load_lds_dwordx4 v[200:201], off
	s_waitcnt vmcnt(8)
	s_waitcnt lgkmcnt(0)
	s_barrier
	s_setprio 1
	v_mfma_f32_16x16x32_bf16 v[142:145], v[156:159], v[208:211], v[142:145]
	v_mfma_f32_16x16x32_bf16 v[138:141], v[174:177], v[208:211], v[138:141]
	v_mfma_f32_16x16x32_bf16 v[126:129], v[156:159], v[216:219], v[126:129]
	v_mfma_f32_16x16x32_bf16 v[122:125], v[174:177], v[216:219], v[122:125]
	v_mfma_f32_16x16x32_bf16 v[110:113], v[156:159], v[224:227], v[110:113]
	v_mfma_f32_16x16x32_bf16 v[106:109], v[174:177], v[224:227], v[106:109]
	v_mfma_f32_16x16x32_bf16 v[94:97], v[156:159], v[238:241], v[94:97]
	v_mfma_f32_16x16x32_bf16 v[90:93], v[174:177], v[238:241], v[90:93]
	v_mfma_f32_16x16x32_bf16 v[142:145], v[170:173], v[212:215], v[142:145]
	v_mfma_f32_16x16x32_bf16 v[138:141], v[178:181], v[212:215], v[138:141]
	v_mfma_f32_16x16x32_bf16 v[126:129], v[170:173], v[220:223], v[126:129]
	v_mfma_f32_16x16x32_bf16 v[122:125], v[178:181], v[220:223], v[122:125]
	v_mfma_f32_16x16x32_bf16 v[110:113], v[170:173], v[228:231], v[110:113]
	v_mfma_f32_16x16x32_bf16 v[106:109], v[178:181], v[228:231], v[106:109]
	v_mfma_f32_16x16x32_bf16 v[94:97], v[170:173], v[242:245], v[94:97]
	v_mfma_f32_16x16x32_bf16 v[90:93], v[178:181], v[242:245], v[90:93]
	v_mfma_f32_16x16x32_bf16 v[134:137], v[182:185], v[208:211], v[134:137]
	v_mfma_f32_16x16x32_bf16 v[130:133], v[190:193], v[208:211], v[130:133]
	v_mfma_f32_16x16x32_bf16 v[118:121], v[182:185], v[216:219], v[118:121]
	v_mfma_f32_16x16x32_bf16 v[114:117], v[190:193], v[216:219], v[114:117]
	v_mfma_f32_16x16x32_bf16 v[102:105], v[182:185], v[224:227], v[102:105]
	v_mfma_f32_16x16x32_bf16 v[98:101], v[190:193], v[224:227], v[98:101]
	v_mfma_f32_16x16x32_bf16 v[86:89], v[182:185], v[238:241], v[86:89]
	v_mfma_f32_16x16x32_bf16 v[82:85], v[190:193], v[238:241], v[82:85]
	v_mfma_f32_16x16x32_bf16 v[134:137], v[186:189], v[212:215], v[134:137]
	v_mfma_f32_16x16x32_bf16 v[130:133], v[204:207], v[212:215], v[130:133]
	v_mfma_f32_16x16x32_bf16 v[118:121], v[186:189], v[220:223], v[118:121]
	v_mfma_f32_16x16x32_bf16 v[114:117], v[204:207], v[220:223], v[114:117]
	v_mfma_f32_16x16x32_bf16 v[102:105], v[186:189], v[228:231], v[102:105]
	v_mfma_f32_16x16x32_bf16 v[98:101], v[204:207], v[228:231], v[98:101]
	v_mfma_f32_16x16x32_bf16 v[86:89], v[186:189], v[242:245], v[86:89]
	v_mfma_f32_16x16x32_bf16 v[82:85], v[204:207], v[242:245], v[82:85]
	s_setprio 0
	s_barrier
	s_mov_b32 m0, s60
	v_lshl_add_u64 v[200:201], v[232:233], 0, s[80:81]
	s_add_u32 s72, vcc_lo, 0x40080
	ds_read_b128 v[208:211], v169 offset:49152
	ds_read_b128 v[212:215], v169 offset:50176
	ds_read_b128 v[216:219], v169 offset:51200
	ds_read_b128 v[220:223], v169 offset:52224
	ds_read_b128 v[224:227], v169 offset:53248
	ds_read_b128 v[228:231], v169 offset:54272
	ds_read_b128 v[238:241], v169 offset:55296
	ds_read_b128 v[242:245], v169 offset:56320
	global_load_lds_dwordx4 v[200:201], off
	v_lshl_add_u64 v[200:201], v[246:247], 0, s[80:81]
	s_mov_b32 m0, s61
	s_addc_u32 s73, vcc_hi, 0
	global_load_lds_dwordx4 v[200:201], off
	v_lshl_add_u64 v[200:201], s[72:73], 0, v[0:1]
	s_mov_b32 m0, s66
	s_nop 0
	global_load_lds_dwordx4 v[200:201], off
	v_lshl_add_u64 v[200:201], s[72:73], 0, v[150:151]
	s_mov_b32 m0, s83
	s_nop 0
	global_load_lds_dwordx4 v[200:201], off
	v_lshl_add_u64 v[200:201], v[248:249], 0, s[80:81]
	s_mov_b32 m0, s62
	s_nop 0
	global_load_lds_dwordx4 v[200:201], off
	v_lshl_add_u64 v[200:201], v[250:251], 0, s[80:81]
	s_mov_b32 m0, s63
	s_nop 0
	global_load_lds_dwordx4 v[200:201], off
	s_waitcnt vmcnt(8)
	s_waitcnt lgkmcnt(0)
	s_barrier
	s_setprio 1
	v_mfma_f32_16x16x32_bf16 v[78:81], v[156:159], v[208:211], v[78:81]
	v_mfma_f32_16x16x32_bf16 v[74:77], v[174:177], v[208:211], v[74:77]
	v_mfma_f32_16x16x32_bf16 v[66:69], v[156:159], v[216:219], v[66:69]
	v_mfma_f32_16x16x32_bf16 v[58:61], v[174:177], v[216:219], v[58:61]
	v_mfma_f32_16x16x32_bf16 v[46:49], v[156:159], v[224:227], v[46:49]
	v_mfma_f32_16x16x32_bf16 v[42:45], v[174:177], v[224:227], v[42:45]
	v_mfma_f32_16x16x32_bf16 v[30:33], v[156:159], v[238:241], v[30:33]
	v_mfma_f32_16x16x32_bf16 v[26:29], v[174:177], v[238:241], v[26:29]
	v_mfma_f32_16x16x32_bf16 v[78:81], v[170:173], v[212:215], v[78:81]
	v_mfma_f32_16x16x32_bf16 v[74:77], v[178:181], v[212:215], v[74:77]
	v_mfma_f32_16x16x32_bf16 v[66:69], v[170:173], v[220:223], v[66:69]
	v_mfma_f32_16x16x32_bf16 v[58:61], v[178:181], v[220:223], v[58:61]
	v_mfma_f32_16x16x32_bf16 v[46:49], v[170:173], v[228:231], v[46:49]
	v_mfma_f32_16x16x32_bf16 v[42:45], v[178:181], v[228:231], v[42:45]
	v_mfma_f32_16x16x32_bf16 v[30:33], v[170:173], v[242:245], v[30:33]
	v_mfma_f32_16x16x32_bf16 v[26:29], v[178:181], v[242:245], v[26:29]
	v_mfma_f32_16x16x32_bf16 v[70:73], v[182:185], v[208:211], v[70:73]
	v_mfma_f32_16x16x32_bf16 v[62:65], v[190:193], v[208:211], v[62:65]
	v_mfma_f32_16x16x32_bf16 v[54:57], v[182:185], v[216:219], v[54:57]
	v_mfma_f32_16x16x32_bf16 v[50:53], v[190:193], v[216:219], v[50:53]
	v_mfma_f32_16x16x32_bf16 v[38:41], v[182:185], v[224:227], v[38:41]
	v_mfma_f32_16x16x32_bf16 v[34:37], v[190:193], v[224:227], v[34:37]
	v_mfma_f32_16x16x32_bf16 v[22:25], v[182:185], v[238:241], v[22:25]
	v_mfma_f32_16x16x32_bf16 v[18:21], v[190:193], v[238:241], v[18:21]
	v_mfma_f32_16x16x32_bf16 v[70:73], v[186:189], v[212:215], v[70:73]
	v_mfma_f32_16x16x32_bf16 v[62:65], v[204:207], v[212:215], v[62:65]
	v_mfma_f32_16x16x32_bf16 v[54:57], v[186:189], v[220:223], v[54:57]
	v_mfma_f32_16x16x32_bf16 v[50:53], v[204:207], v[220:223], v[50:53]
	v_mfma_f32_16x16x32_bf16 v[38:41], v[186:189], v[228:231], v[38:41]
	v_mfma_f32_16x16x32_bf16 v[34:37], v[204:207], v[228:231], v[34:37]
	v_mfma_f32_16x16x32_bf16 v[22:25], v[186:189], v[242:245], v[22:25]
	v_mfma_f32_16x16x32_bf16 v[18:21], v[204:207], v[242:245], v[18:21]
	s_setprio 0
	s_barrier
	s_add_i32 s42, s42, 2
	s_add_u32 s44, s44, 0x100
	s_addc_u32 s45, s45, 0
	s_add_u32 s64, s64, 0x100
	s_addc_u32 s65, s65, 0
	s_cmp_gt_u32 s42, 13
	s_cbranch_scc0 .LBB0_596
	s_and_b64 vcc, exec, s[74:75]
	s_cbranch_vccz .LBB0_600
	s_barrier
	s_and_b64 s[44:45], s[34:35], s[38:39]
	s_and_saveexec_b64 s[76:77], s[44:45]
	s_cbranch_execnz .LBB0_601

.LBB0_896:
	s_add_u32 s25, s18, s24
	s_addc_u32 s30, s19, 0
	s_add_u32 s28, s25, 0x100
	s_addc_u32 s29, s30, 0
	s_and_b64 s[26:27], s[22:23], exec
	s_cselect_b32 s27, s13, s29
	s_cselect_b32 s26, s12, s28
	s_add_u32 s24, s16, s24
	s_addc_u32 s28, s17, 0
	s_add_u32 s24, s24, 0x100
	s_addc_u32 s28, s28, 0
	s_and_b64 s[22:23], s[22:23], exec
	v_add_u32_e32 v140, s38, v143
	s_cselect_b32 s29, s62, s28
	s_cselect_b32 s28, s63, s24
	s_add_u32 s34, s25, 0x2c0080
	ds_read_b128 v[136:139], v140
	ds_read_b128 v[158:161], v140 offset:1024
	ds_read_b128 v[162:165], v140 offset:2048
	ds_read_b128 v[166:169], v140 offset:3072
	v_add_u32_e32 v140, s41, v143
	s_addc_u32 s35, s30, 0
	s_add_i32 m0, s44, 0xc000
	s_add_i32 s64, s44, 0xe000
	ds_read_b128 v[170:173], v140
	ds_read_b128 v[174:177], v140 offset:1024
	ds_read_b128 v[178:181], v140 offset:2048
	ds_read_b128 v[182:185], v140 offset:3072
	s_add_u32 s30, s28, 0x40000
	s_addc_u32 s31, s29, 0
	s_add_u32 s24, s26, 0x2c0000
	s_addc_u32 s25, s27, 0
	s_add_u32 s22, s28, 0x40080
	s_addc_u32 s23, s29, 0
	v_lshl_add_u64 v[140:141], s[34:35], 0, v[134:135]
	ds_read_b128 v[186:189], v155
	ds_read_b128 v[190:193], v155 offset:1024
	ds_read_b128 v[204:207], v155 offset:2048
	ds_read_b128 v[208:211], v155 offset:3072
	ds_read_b128 v[212:215], v155 offset:4096
	ds_read_b128 v[216:219], v155 offset:5120
	ds_read_b128 v[220:223], v155 offset:6144
	ds_read_b128 v[224:227], v155 offset:7168
	global_load_lds_dwordx4 v[140:141], off
	v_lshl_add_u64 v[140:141], s[34:35], 0, v[132:133]
	s_mov_b32 m0, s64
	s_nop 0
	global_load_lds_dwordx4 v[140:141], off
	s_waitcnt vmcnt(8)
	s_waitcnt lgkmcnt(0)
	s_barrier
	s_setprio 1
	v_mfma_f32_16x16x32_bf16 v[126:129], v[136:139], v[186:189], v[126:129]
	v_mfma_f32_16x16x32_bf16 v[122:125], v[162:165], v[186:189], v[122:125]
	v_mfma_f32_16x16x32_bf16 v[110:113], v[136:139], v[204:207], v[110:113]
	v_mfma_f32_16x16x32_bf16 v[106:109], v[162:165], v[204:207], v[106:109]
	v_mfma_f32_16x16x32_bf16 v[94:97], v[136:139], v[212:215], v[94:97]
	v_mfma_f32_16x16x32_bf16 v[90:93], v[162:165], v[212:215], v[90:93]
	v_mfma_f32_16x16x32_bf16 v[78:81], v[136:139], v[220:223], v[78:81]
	v_mfma_f32_16x16x32_bf16 v[74:77], v[162:165], v[220:223], v[74:77]
	v_mfma_f32_16x16x32_bf16 v[126:129], v[158:161], v[190:193], v[126:129]
	v_mfma_f32_16x16x32_bf16 v[122:125], v[166:169], v[190:193], v[122:125]
	v_mfma_f32_16x16x32_bf16 v[110:113], v[158:161], v[208:211], v[110:113]
	v_mfma_f32_16x16x32_bf16 v[106:109], v[166:169], v[208:211], v[106:109]
	v_mfma_f32_16x16x32_bf16 v[94:97], v[158:161], v[216:219], v[94:97]
	v_mfma_f32_16x16x32_bf16 v[90:93], v[166:169], v[216:219], v[90:93]
	v_mfma_f32_16x16x32_bf16 v[78:81], v[158:161], v[224:227], v[78:81]
	v_mfma_f32_16x16x32_bf16 v[74:77], v[166:169], v[224:227], v[74:77]
	v_mfma_f32_16x16x32_bf16 v[118:121], v[170:173], v[186:189], v[118:121]
	v_mfma_f32_16x16x32_bf16 v[114:117], v[178:181], v[186:189], v[114:117]
	v_mfma_f32_16x16x32_bf16 v[102:105], v[170:173], v[204:207], v[102:105]
	v_mfma_f32_16x16x32_bf16 v[98:101], v[178:181], v[204:207], v[98:101]
	v_mfma_f32_16x16x32_bf16 v[86:89], v[170:173], v[212:215], v[86:89]
	v_mfma_f32_16x16x32_bf16 v[82:85], v[178:181], v[212:215], v[82:85]
	v_mfma_f32_16x16x32_bf16 v[70:73], v[170:173], v[220:223], v[70:73]
	v_mfma_f32_16x16x32_bf16 v[66:69], v[178:181], v[220:223], v[66:69]
	v_mfma_f32_16x16x32_bf16 v[118:121], v[174:177], v[190:193], v[118:121]
	v_mfma_f32_16x16x32_bf16 v[114:117], v[182:185], v[190:193], v[114:117]
	v_mfma_f32_16x16x32_bf16 v[102:105], v[174:177], v[208:211], v[102:105]
	v_mfma_f32_16x16x32_bf16 v[98:101], v[182:185], v[208:211], v[98:101]
	v_mfma_f32_16x16x32_bf16 v[86:89], v[174:177], v[216:219], v[86:89]
	v_mfma_f32_16x16x32_bf16 v[82:85], v[182:185], v[216:219], v[82:85]
	v_mfma_f32_16x16x32_bf16 v[70:73], v[174:177], v[224:227], v[70:73]
	v_mfma_f32_16x16x32_bf16 v[66:69], v[182:185], v[224:227], v[66:69]
	s_setprio 0
	s_barrier
	s_mov_b32 m0, s39
	v_lshl_add_u64 v[140:141], s[28:29], 0, v[0:1]
	ds_read_b128 v[186:189], v155 offset:16384
	ds_read_b128 v[190:193], v155 offset:17408
	ds_read_b128 v[204:207], v155 offset:18432
	ds_read_b128 v[208:211], v155 offset:19456
	ds_read_b128 v[212:215], v155 offset:20480
	ds_read_b128 v[216:219], v155 offset:21504
	ds_read_b128 v[220:223], v155 offset:22528
	ds_read_b128 v[224:227], v155 offset:23552
	global_load_lds_dwordx4 v[140:141], off
	v_lshl_add_u64 v[200:201], s[28:29], 0, v[130:131]
	s_mov_b32 m0, s40
	v_lshl_add_u64 v[228:229], s[30:31], 0, v[0:1]
	global_load_lds_dwordx4 v[200:201], off
	s_mov_b32 m0, s42
	v_lshl_add_u64 v[230:231], s[26:27], 0, v[132:133]
	global_load_lds_dwordx4 v[228:229], off
	v_lshl_add_u64 v[228:229], s[30:31], 0, v[130:131]
	s_mov_b32 m0, s43
	s_nop 0
	global_load_lds_dwordx4 v[228:229], off
	v_lshl_add_u64 v[228:229], s[26:27], 0, v[134:135]
	s_mov_b32 m0, s44
	s_nop 0
	global_load_lds_dwordx4 v[228:229], off
	s_mov_b32 m0, s45
	s_nop 0
	global_load_lds_dwordx4 v[230:231], off
	s_waitcnt vmcnt(8)
	s_waitcnt lgkmcnt(0)
	s_barrier
	s_setprio 1
	v_mfma_f32_16x16x32_bf16 v[62:65], v[136:139], v[186:189], v[62:65]
	v_mfma_f32_16x16x32_bf16 v[58:61], v[162:165], v[186:189], v[58:61]
	v_mfma_f32_16x16x32_bf16 v[46:49], v[136:139], v[204:207], v[46:49]
	v_mfma_f32_16x16x32_bf16 v[42:45], v[162:165], v[204:207], v[42:45]
	v_mfma_f32_16x16x32_bf16 v[30:33], v[136:139], v[212:215], v[30:33]
	v_mfma_f32_16x16x32_bf16 v[26:29], v[162:165], v[212:215], v[26:29]
	v_mfma_f32_16x16x32_bf16 v[14:17], v[136:139], v[220:223], v[14:17]
	v_mfma_f32_16x16x32_bf16 v[10:13], v[162:165], v[220:223], v[10:13]
	v_mfma_f32_16x16x32_bf16 v[62:65], v[158:161], v[190:193], v[62:65]
	v_mfma_f32_16x16x32_bf16 v[58:61], v[166:169], v[190:193], v[58:61]
	v_mfma_f32_16x16x32_bf16 v[46:49], v[158:161], v[208:211], v[46:49]
	v_mfma_f32_16x16x32_bf16 v[42:45], v[166:169], v[208:211], v[42:45]
	v_mfma_f32_16x16x32_bf16 v[30:33], v[158:161], v[216:219], v[30:33]
	v_mfma_f32_16x16x32_bf16 v[26:29], v[166:169], v[216:219], v[26:29]
	v_mfma_f32_16x16x32_bf16 v[14:17], v[158:161], v[224:227], v[14:17]
	v_mfma_f32_16x16x32_bf16 v[10:13], v[166:169], v[224:227], v[10:13]
	v_mfma_f32_16x16x32_bf16 v[54:57], v[170:173], v[186:189], v[54:57]
	v_mfma_f32_16x16x32_bf16 v[50:53], v[178:181], v[186:189], v[50:53]
	v_mfma_f32_16x16x32_bf16 v[38:41], v[170:173], v[204:207], v[38:41]
	v_mfma_f32_16x16x32_bf16 v[34:37], v[178:181], v[204:207], v[34:37]
	v_mfma_f32_16x16x32_bf16 v[22:25], v[170:173], v[212:215], v[22:25]
	v_mfma_f32_16x16x32_bf16 v[18:21], v[178:181], v[212:215], v[18:21]
	v_mfma_f32_16x16x32_bf16 v[6:9], v[170:173], v[220:223], v[6:9]
	v_mfma_f32_16x16x32_bf16 v[2:5], v[178:181], v[220:223], v[2:5]
	v_mfma_f32_16x16x32_bf16 v[54:57], v[174:177], v[190:193], v[54:57]
	v_mfma_f32_16x16x32_bf16 v[50:53], v[182:185], v[190:193], v[50:53]
	v_mfma_f32_16x16x32_bf16 v[38:41], v[174:177], v[208:211], v[38:41]
	v_mfma_f32_16x16x32_bf16 v[34:37], v[182:185], v[208:211], v[34:37]
	v_mfma_f32_16x16x32_bf16 v[22:25], v[174:177], v[216:219], v[22:25]
	v_mfma_f32_16x16x32_bf16 v[18:21], v[182:185], v[216:219], v[18:21]
	v_mfma_f32_16x16x32_bf16 v[6:9], v[174:177], v[224:227], v[6:9]
	v_mfma_f32_16x16x32_bf16 v[2:5], v[182:185], v[224:227], v[2:5]
	s_setprio 0
	s_barrier
	v_add_u32_e32 v157, s48, v143
	ds_read_b128 v[136:139], v157
	ds_read_b128 v[158:161], v157 offset:1024
	ds_read_b128 v[162:165], v157 offset:2048
	ds_read_b128 v[166:169], v157 offset:3072
	v_add_u32_e32 v157, s53, v143
	ds_read_b128 v[170:173], v157
	ds_read_b128 v[174:177], v157 offset:1024
	ds_read_b128 v[178:181], v157 offset:2048
	ds_read_b128 v[182:185], v157 offset:3072
	s_mov_b32 m0, s46
	v_lshl_add_u64 v[232:233], s[24:25], 0, v[134:135]
	ds_read_b128 v[186:189], v155 offset:32768
	ds_read_b128 v[190:193], v155 offset:33792
	ds_read_b128 v[204:207], v155 offset:34816
	ds_read_b128 v[208:211], v155 offset:35840
	ds_read_b128 v[212:215], v155 offset:36864
	ds_read_b128 v[216:219], v155 offset:37888
	ds_read_b128 v[220:223], v155 offset:38912
	ds_read_b128 v[224:227], v155 offset:39936
	global_load_lds_dwordx4 v[232:233], off
	v_lshl_add_u64 v[232:233], s[24:25], 0, v[132:133]
	s_mov_b32 m0, s47
	s_nop 0
	global_load_lds_dwordx4 v[232:233], off
	s_waitcnt vmcnt(8)
	s_waitcnt lgkmcnt(0)
	s_barrier
	s_setprio 1
	v_mfma_f32_16x16x32_bf16 v[126:129], v[136:139], v[186:189], v[126:129]
	v_mfma_f32_16x16x32_bf16 v[122:125], v[162:165], v[186:189], v[122:125]
	v_mfma_f32_16x16x32_bf16 v[110:113], v[136:139], v[204:207], v[110:113]
	v_mfma_f32_16x16x32_bf16 v[106:109], v[162:165], v[204:207], v[106:109]
	v_mfma_f32_16x16x32_bf16 v[94:97], v[136:139], v[212:215], v[94:97]
	v_mfma_f32_16x16x32_bf16 v[90:93], v[162:165], v[212:215], v[90:93]
	v_mfma_f32_16x16x32_bf16 v[78:81], v[136:139], v[220:223], v[78:81]
	v_mfma_f32_16x16x32_bf16 v[74:77], v[162:165], v[220:223], v[74:77]
	v_mfma_f32_16x16x32_bf16 v[126:129], v[158:161], v[190:193], v[126:129]
	v_mfma_f32_16x16x32_bf16 v[122:125], v[166:169], v[190:193], v[122:125]
	v_mfma_f32_16x16x32_bf16 v[110:113], v[158:161], v[208:211], v[110:113]
	v_mfma_f32_16x16x32_bf16 v[106:109], v[166:169], v[208:211], v[106:109]
	v_mfma_f32_16x16x32_bf16 v[94:97], v[158:161], v[216:219], v[94:97]
	v_mfma_f32_16x16x32_bf16 v[90:93], v[166:169], v[216:219], v[90:93]
	v_mfma_f32_16x16x32_bf16 v[78:81], v[158:161], v[224:227], v[78:81]
	v_mfma_f32_16x16x32_bf16 v[74:77], v[166:169], v[224:227], v[74:77]
	v_mfma_f32_16x16x32_bf16 v[118:121], v[170:173], v[186:189], v[118:121]
	v_mfma_f32_16x16x32_bf16 v[114:117], v[178:181], v[186:189], v[114:117]
	v_mfma_f32_16x16x32_bf16 v[102:105], v[170:173], v[204:207], v[102:105]
	v_mfma_f32_16x16x32_bf16 v[98:101], v[178:181], v[204:207], v[98:101]
	v_mfma_f32_16x16x32_bf16 v[86:89], v[170:173], v[212:215], v[86:89]
	v_mfma_f32_16x16x32_bf16 v[82:85], v[178:181], v[212:215], v[82:85]
	v_mfma_f32_16x16x32_bf16 v[70:73], v[170:173], v[220:223], v[70:73]
	v_mfma_f32_16x16x32_bf16 v[66:69], v[178:181], v[220:223], v[66:69]
	v_mfma_f32_16x16x32_bf16 v[118:121], v[174:177], v[190:193], v[118:121]
	v_mfma_f32_16x16x32_bf16 v[114:117], v[182:185], v[190:193], v[114:117]
	v_mfma_f32_16x16x32_bf16 v[102:105], v[174:177], v[208:211], v[102:105]
	v_mfma_f32_16x16x32_bf16 v[98:101], v[182:185], v[208:211], v[98:101]
	v_mfma_f32_16x16x32_bf16 v[86:89], v[174:177], v[216:219], v[86:89]
	v_mfma_f32_16x16x32_bf16 v[82:85], v[182:185], v[216:219], v[82:85]
	v_mfma_f32_16x16x32_bf16 v[70:73], v[174:177], v[224:227], v[70:73]
	v_mfma_f32_16x16x32_bf16 v[66:69], v[182:185], v[224:227], v[66:69]
	s_setprio 0
	s_barrier
	s_mov_b32 m0, s49
	v_lshl_add_u64 v[140:141], v[140:141], 0, s[80:81]
	ds_read_b128 v[186:189], v155 offset:49152
	ds_read_b128 v[190:193], v155 offset:50176
	ds_read_b128 v[204:207], v155 offset:51200
	ds_read_b128 v[208:211], v155 offset:52224
	ds_read_b128 v[212:215], v155 offset:53248
	ds_read_b128 v[216:219], v155 offset:54272
	ds_read_b128 v[220:223], v155 offset:55296
	ds_read_b128 v[224:227], v155 offset:56320
	global_load_lds_dwordx4 v[140:141], off
	v_lshl_add_u64 v[140:141], v[200:201], 0, s[80:81]
	s_mov_b32 m0, s50
	s_nop 0
	global_load_lds_dwordx4 v[140:141], off
	v_lshl_add_u64 v[140:141], s[22:23], 0, v[0:1]
	s_mov_b32 m0, s54
	s_nop 0
	global_load_lds_dwordx4 v[140:141], off
	v_lshl_add_u64 v[140:141], s[22:23], 0, v[130:131]
	s_mov_b32 m0, s55
	s_nop 0
	global_load_lds_dwordx4 v[140:141], off
	v_lshl_add_u64 v[140:141], v[228:229], 0, s[80:81]
	s_mov_b32 m0, s51
	s_nop 0
	global_load_lds_dwordx4 v[140:141], off
	v_lshl_add_u64 v[140:141], v[230:231], 0, s[80:81]
	s_mov_b32 m0, s52
	s_nop 0
	global_load_lds_dwordx4 v[140:141], off
	s_waitcnt vmcnt(8)
	s_waitcnt lgkmcnt(0)
	s_barrier
	s_setprio 1
	v_mfma_f32_16x16x32_bf16 v[62:65], v[136:139], v[186:189], v[62:65]
	v_mfma_f32_16x16x32_bf16 v[58:61], v[162:165], v[186:189], v[58:61]
	v_mfma_f32_16x16x32_bf16 v[46:49], v[136:139], v[204:207], v[46:49]
	v_mfma_f32_16x16x32_bf16 v[42:45], v[162:165], v[204:207], v[42:45]
	v_mfma_f32_16x16x32_bf16 v[30:33], v[136:139], v[212:215], v[30:33]
	v_mfma_f32_16x16x32_bf16 v[26:29], v[162:165], v[212:215], v[26:29]
	v_mfma_f32_16x16x32_bf16 v[14:17], v[136:139], v[220:223], v[14:17]
	v_mfma_f32_16x16x32_bf16 v[10:13], v[162:165], v[220:223], v[10:13]
	v_mfma_f32_16x16x32_bf16 v[62:65], v[158:161], v[190:193], v[62:65]
	v_mfma_f32_16x16x32_bf16 v[58:61], v[166:169], v[190:193], v[58:61]
	v_mfma_f32_16x16x32_bf16 v[46:49], v[158:161], v[208:211], v[46:49]
	v_mfma_f32_16x16x32_bf16 v[42:45], v[166:169], v[208:211], v[42:45]
	v_mfma_f32_16x16x32_bf16 v[30:33], v[158:161], v[216:219], v[30:33]
	v_mfma_f32_16x16x32_bf16 v[26:29], v[166:169], v[216:219], v[26:29]
	v_mfma_f32_16x16x32_bf16 v[14:17], v[158:161], v[224:227], v[14:17]
	v_mfma_f32_16x16x32_bf16 v[10:13], v[166:169], v[224:227], v[10:13]
	v_mfma_f32_16x16x32_bf16 v[54:57], v[170:173], v[186:189], v[54:57]
	v_mfma_f32_16x16x32_bf16 v[50:53], v[178:181], v[186:189], v[50:53]
	v_mfma_f32_16x16x32_bf16 v[38:41], v[170:173], v[204:207], v[38:41]
	v_mfma_f32_16x16x32_bf16 v[34:37], v[178:181], v[204:207], v[34:37]
	v_mfma_f32_16x16x32_bf16 v[22:25], v[170:173], v[212:215], v[22:25]
	v_mfma_f32_16x16x32_bf16 v[18:21], v[178:181], v[212:215], v[18:21]
	v_mfma_f32_16x16x32_bf16 v[6:9], v[170:173], v[220:223], v[6:9]
	v_mfma_f32_16x16x32_bf16 v[2:5], v[178:181], v[220:223], v[2:5]
	v_mfma_f32_16x16x32_bf16 v[54:57], v[174:177], v[190:193], v[54:57]
	v_mfma_f32_16x16x32_bf16 v[50:53], v[182:185], v[190:193], v[50:53]
	v_mfma_f32_16x16x32_bf16 v[38:41], v[174:177], v[208:211], v[38:41]
	v_mfma_f32_16x16x32_bf16 v[34:37], v[182:185], v[208:211], v[34:37]
	v_mfma_f32_16x16x32_bf16 v[22:25], v[174:177], v[216:219], v[22:25]
	v_mfma_f32_16x16x32_bf16 v[18:21], v[182:185], v[216:219], v[18:21]
	v_mfma_f32_16x16x32_bf16 v[6:9], v[174:177], v[224:227], v[6:9]
	v_mfma_f32_16x16x32_bf16 v[2:5], v[182:185], v[224:227], v[2:5]
	s_setprio 0
	s_barrier
	s_movk_i32 s24, 0x100
	s_andn2_b64 vcc, exec, s[20:21]
	s_mov_b64 s[22:23], -1
	s_mov_b64 s[20:21], 0
	s_cbranch_vccz .LBB0_896
	s_and_b64 vcc, exec, s[8:9]
	s_cbranch_vccz .LBB0_899
	s_barrier

.LBB0_1010:
	s_add_u32 s36, s22, s17
	s_addc_u32 s37, s23, 0
	s_add_u32 s30, s36, 0x100
	s_addc_u32 s31, s37, 0
	s_and_b64 s[28:29], s[26:27], exec
	s_cselect_b32 s31, s15, s31
	s_cselect_b32 s30, s14, s30
	s_add_u32 s17, s20, s17
	s_addc_u32 s28, s21, 0
	s_add_u32 s17, s17, 0x100
	s_addc_u32 s28, s28, 0
	s_and_b64 s[26:27], s[26:27], exec
	s_cselect_b32 s35, s19, s28
	s_cselect_b32 s34, s18, s17
	s_add_u32 s38, s36, 0x40080
	v_add_u32_e32 v86, s5, v223
	v_add_u32_e32 v158, s53, v223
	s_addc_u32 s39, s37, 0
	s_add_i32 m0, s56, 0xc000
	s_add_i32 s17, s56, 0xe000
	ds_read_b128 v[70:73], v86
	ds_read_b128 v[78:81], v86 offset:1024
	ds_read_b128 v[82:85], v86 offset:2048
	ds_read_b128 v[86:89], v86 offset:3072
	ds_read_b128 v[146:149], v158
	ds_read_b128 v[150:153], v158 offset:1024
	ds_read_b128 v[154:157], v158 offset:2048
	ds_read_b128 v[158:161], v158 offset:3072
	s_add_u32 s36, s34, 0x10000
	s_addc_u32 s37, s35, 0
	s_add_u32 s28, s30, 0x40000
	s_addc_u32 s29, s31, 0
	s_add_u32 s26, s34, 0x10080
	s_addc_u32 s27, s35, 0
	v_lshl_add_u64 v[200:201], s[38:39], 0, v[208:209]
	ds_read_b128 v[162:165], v225
	ds_read_b128 v[166:169], v225 offset:1024
	ds_read_b128 v[170:173], v225 offset:2048
	ds_read_b128 v[174:177], v225 offset:3072
	ds_read_b128 v[178:181], v225 offset:4096
	ds_read_b128 v[182:185], v225 offset:5120
	ds_read_b128 v[186:189], v225 offset:6144
	ds_read_b128 v[190:193], v225 offset:7168
	global_load_lds_dwordx4 v[200:201], off
	v_lshl_add_u64 v[200:201], s[38:39], 0, v[206:207]
	s_mov_b32 m0, s17
	s_nop 0
	global_load_lds_dwordx4 v[200:201], off
	s_waitcnt vmcnt(8)
	s_waitcnt lgkmcnt(0)
	s_barrier
	s_setprio 1
	v_mfma_f32_16x16x32_bf16 v[142:145], v[70:73], v[162:165], v[142:145]
	v_mfma_f32_16x16x32_bf16 v[138:141], v[82:85], v[162:165], v[138:141]
	v_mfma_f32_16x16x32_bf16 v[126:129], v[70:73], v[170:173], v[126:129]
	v_mfma_f32_16x16x32_bf16 v[122:125], v[82:85], v[170:173], v[122:125]
	v_mfma_f32_16x16x32_bf16 v[110:113], v[70:73], v[178:181], v[110:113]
	v_mfma_f32_16x16x32_bf16 v[106:109], v[82:85], v[178:181], v[106:109]
	v_mfma_f32_16x16x32_bf16 v[94:97], v[70:73], v[186:189], v[94:97]
	v_mfma_f32_16x16x32_bf16 v[90:93], v[82:85], v[186:189], v[90:93]
	v_mfma_f32_16x16x32_bf16 v[142:145], v[78:81], v[166:169], v[142:145]
	v_mfma_f32_16x16x32_bf16 v[138:141], v[86:89], v[166:169], v[138:141]
	v_mfma_f32_16x16x32_bf16 v[126:129], v[78:81], v[174:177], v[126:129]
	v_mfma_f32_16x16x32_bf16 v[122:125], v[86:89], v[174:177], v[122:125]
	v_mfma_f32_16x16x32_bf16 v[110:113], v[78:81], v[182:185], v[110:113]
	v_mfma_f32_16x16x32_bf16 v[106:109], v[86:89], v[182:185], v[106:109]
	v_mfma_f32_16x16x32_bf16 v[94:97], v[78:81], v[190:193], v[94:97]
	v_mfma_f32_16x16x32_bf16 v[90:93], v[86:89], v[190:193], v[90:93]
	v_mfma_f32_16x16x32_bf16 v[134:137], v[146:149], v[162:165], v[134:137]
	v_mfma_f32_16x16x32_bf16 v[130:133], v[154:157], v[162:165], v[130:133]
	v_mfma_f32_16x16x32_bf16 v[118:121], v[146:149], v[170:173], v[118:121]
	v_mfma_f32_16x16x32_bf16 v[114:117], v[154:157], v[170:173], v[114:117]
	v_mfma_f32_16x16x32_bf16 v[102:105], v[146:149], v[178:181], v[102:105]
	v_mfma_f32_16x16x32_bf16 v[98:101], v[154:157], v[178:181], v[98:101]
	v_mfma_f32_16x16x32_bf16 v[74:77], v[146:149], v[186:189], v[74:77]
	v_mfma_f32_16x16x32_bf16 v[66:69], v[154:157], v[186:189], v[66:69]
	v_mfma_f32_16x16x32_bf16 v[134:137], v[150:153], v[166:169], v[134:137]
	v_mfma_f32_16x16x32_bf16 v[130:133], v[158:161], v[166:169], v[130:133]
	v_mfma_f32_16x16x32_bf16 v[118:121], v[150:153], v[174:177], v[118:121]
	v_mfma_f32_16x16x32_bf16 v[114:117], v[158:161], v[174:177], v[114:117]
	v_mfma_f32_16x16x32_bf16 v[102:105], v[150:153], v[182:185], v[102:105]
	v_mfma_f32_16x16x32_bf16 v[98:101], v[158:161], v[182:185], v[98:101]
	v_mfma_f32_16x16x32_bf16 v[74:77], v[150:153], v[190:193], v[74:77]
	v_mfma_f32_16x16x32_bf16 v[66:69], v[158:161], v[190:193], v[66:69]
	s_setprio 0
	s_barrier
	s_mov_b32 m0, s51
	v_lshl_add_u64 v[200:201], s[34:35], 0, v[0:1]
	ds_read_b128 v[162:165], v225 offset:16384
	ds_read_b128 v[166:169], v225 offset:17408
	ds_read_b128 v[170:173], v225 offset:18432
	ds_read_b128 v[174:177], v225 offset:19456
	ds_read_b128 v[178:181], v225 offset:20480
	ds_read_b128 v[182:185], v225 offset:21504
	ds_read_b128 v[186:189], v225 offset:22528
	ds_read_b128 v[190:193], v225 offset:23552
	global_load_lds_dwordx4 v[200:201], off
	v_lshl_add_u64 v[210:211], s[34:35], 0, v[204:205]
	s_mov_b32 m0, s52
	v_lshl_add_u64 v[212:213], s[36:37], 0, v[0:1]
	global_load_lds_dwordx4 v[210:211], off
	s_mov_b32 m0, s54
	v_lshl_add_u64 v[214:215], s[30:31], 0, v[206:207]
	global_load_lds_dwordx4 v[212:213], off
	v_lshl_add_u64 v[212:213], s[36:37], 0, v[204:205]
	s_mov_b32 m0, s55
	s_nop 0
	global_load_lds_dwordx4 v[212:213], off
	v_lshl_add_u64 v[212:213], s[30:31], 0, v[208:209]
	s_mov_b32 m0, s56
	s_nop 0
	global_load_lds_dwordx4 v[212:213], off
	s_mov_b32 m0, s57
	s_nop 0
	global_load_lds_dwordx4 v[214:215], off
	s_waitcnt vmcnt(8)
	s_waitcnt lgkmcnt(0)
	s_barrier
	s_setprio 1
	v_mfma_f32_16x16x32_bf16 v[62:65], v[70:73], v[162:165], v[62:65]
	v_mfma_f32_16x16x32_bf16 v[58:61], v[82:85], v[162:165], v[58:61]
	v_mfma_f32_16x16x32_bf16 v[46:49], v[70:73], v[170:173], v[46:49]
	v_mfma_f32_16x16x32_bf16 v[42:45], v[82:85], v[170:173], v[42:45]
	v_mfma_f32_16x16x32_bf16 v[30:33], v[70:73], v[178:181], v[30:33]
	v_mfma_f32_16x16x32_bf16 v[26:29], v[82:85], v[178:181], v[26:29]
	v_mfma_f32_16x16x32_bf16 v[14:17], v[70:73], v[186:189], v[14:17]
	v_mfma_f32_16x16x32_bf16 v[10:13], v[82:85], v[186:189], v[10:13]
	v_mfma_f32_16x16x32_bf16 v[62:65], v[78:81], v[166:169], v[62:65]
	v_mfma_f32_16x16x32_bf16 v[58:61], v[86:89], v[166:169], v[58:61]
	v_mfma_f32_16x16x32_bf16 v[46:49], v[78:81], v[174:177], v[46:49]
	v_mfma_f32_16x16x32_bf16 v[42:45], v[86:89], v[174:177], v[42:45]
	v_mfma_f32_16x16x32_bf16 v[30:33], v[78:81], v[182:185], v[30:33]
	v_mfma_f32_16x16x32_bf16 v[26:29], v[86:89], v[182:185], v[26:29]
	v_mfma_f32_16x16x32_bf16 v[14:17], v[78:81], v[190:193], v[14:17]
	v_mfma_f32_16x16x32_bf16 v[10:13], v[86:89], v[190:193], v[10:13]
	v_mfma_f32_16x16x32_bf16 v[54:57], v[146:149], v[162:165], v[54:57]
	v_mfma_f32_16x16x32_bf16 v[50:53], v[154:157], v[162:165], v[50:53]
	v_mfma_f32_16x16x32_bf16 v[38:41], v[146:149], v[170:173], v[38:41]
	v_mfma_f32_16x16x32_bf16 v[34:37], v[154:157], v[170:173], v[34:37]
	v_mfma_f32_16x16x32_bf16 v[22:25], v[146:149], v[178:181], v[22:25]
	v_mfma_f32_16x16x32_bf16 v[18:21], v[154:157], v[178:181], v[18:21]
	v_mfma_f32_16x16x32_bf16 v[6:9], v[146:149], v[186:189], v[6:9]
	v_mfma_f32_16x16x32_bf16 v[2:5], v[154:157], v[186:189], v[2:5]
	v_mfma_f32_16x16x32_bf16 v[54:57], v[150:153], v[166:169], v[54:57]
	v_mfma_f32_16x16x32_bf16 v[50:53], v[158:161], v[166:169], v[50:53]
	v_mfma_f32_16x16x32_bf16 v[38:41], v[150:153], v[174:177], v[38:41]
	v_mfma_f32_16x16x32_bf16 v[34:37], v[158:161], v[174:177], v[34:37]
	v_mfma_f32_16x16x32_bf16 v[22:25], v[150:153], v[182:185], v[22:25]
	v_mfma_f32_16x16x32_bf16 v[18:21], v[158:161], v[182:185], v[18:21]
	v_mfma_f32_16x16x32_bf16 v[6:9], v[150:153], v[190:193], v[6:9]
	v_mfma_f32_16x16x32_bf16 v[2:5], v[158:161], v[190:193], v[2:5]
	s_setprio 0
	s_barrier
	v_add_u32_e32 v86, s66, v223
	v_add_u32_e32 v158, s71, v223
	ds_read_b128 v[70:73], v86
	ds_read_b128 v[78:81], v86 offset:1024
	ds_read_b128 v[82:85], v86 offset:2048
	ds_read_b128 v[86:89], v86 offset:3072
	ds_read_b128 v[146:149], v158
	ds_read_b128 v[150:153], v158 offset:1024
	ds_read_b128 v[154:157], v158 offset:2048
	ds_read_b128 v[158:161], v158 offset:3072
	s_mov_b32 m0, s58
	v_lshl_add_u64 v[216:217], s[28:29], 0, v[208:209]
	ds_read_b128 v[162:165], v225 offset:32768
	ds_read_b128 v[166:169], v225 offset:33792
	ds_read_b128 v[170:173], v225 offset:34816
	ds_read_b128 v[174:177], v225 offset:35840
	ds_read_b128 v[178:181], v225 offset:36864
	ds_read_b128 v[182:185], v225 offset:37888
	ds_read_b128 v[186:189], v225 offset:38912
	ds_read_b128 v[190:193], v225 offset:39936
	global_load_lds_dwordx4 v[216:217], off
	v_lshl_add_u64 v[216:217], s[28:29], 0, v[206:207]
	s_mov_b32 m0, s59
	s_nop 0
	global_load_lds_dwordx4 v[216:217], off
	s_waitcnt vmcnt(8)
	s_waitcnt lgkmcnt(0)
	s_barrier
	s_setprio 1
	v_mfma_f32_16x16x32_bf16 v[142:145], v[70:73], v[162:165], v[142:145]
	v_mfma_f32_16x16x32_bf16 v[138:141], v[82:85], v[162:165], v[138:141]
	v_mfma_f32_16x16x32_bf16 v[126:129], v[70:73], v[170:173], v[126:129]
	v_mfma_f32_16x16x32_bf16 v[122:125], v[82:85], v[170:173], v[122:125]
	v_mfma_f32_16x16x32_bf16 v[110:113], v[70:73], v[178:181], v[110:113]
	v_mfma_f32_16x16x32_bf16 v[106:109], v[82:85], v[178:181], v[106:109]
	v_mfma_f32_16x16x32_bf16 v[94:97], v[70:73], v[186:189], v[94:97]
	v_mfma_f32_16x16x32_bf16 v[90:93], v[82:85], v[186:189], v[90:93]
	v_mfma_f32_16x16x32_bf16 v[142:145], v[78:81], v[166:169], v[142:145]
	v_mfma_f32_16x16x32_bf16 v[138:141], v[86:89], v[166:169], v[138:141]
	v_mfma_f32_16x16x32_bf16 v[126:129], v[78:81], v[174:177], v[126:129]
	v_mfma_f32_16x16x32_bf16 v[122:125], v[86:89], v[174:177], v[122:125]
	v_mfma_f32_16x16x32_bf16 v[110:113], v[78:81], v[182:185], v[110:113]
	v_mfma_f32_16x16x32_bf16 v[106:109], v[86:89], v[182:185], v[106:109]
	v_mfma_f32_16x16x32_bf16 v[94:97], v[78:81], v[190:193], v[94:97]
	v_mfma_f32_16x16x32_bf16 v[90:93], v[86:89], v[190:193], v[90:93]
	v_mfma_f32_16x16x32_bf16 v[134:137], v[146:149], v[162:165], v[134:137]
	v_mfma_f32_16x16x32_bf16 v[130:133], v[154:157], v[162:165], v[130:133]
	v_mfma_f32_16x16x32_bf16 v[118:121], v[146:149], v[170:173], v[118:121]
	v_mfma_f32_16x16x32_bf16 v[114:117], v[154:157], v[170:173], v[114:117]
	v_mfma_f32_16x16x32_bf16 v[102:105], v[146:149], v[178:181], v[102:105]
	v_mfma_f32_16x16x32_bf16 v[98:101], v[154:157], v[178:181], v[98:101]
	v_mfma_f32_16x16x32_bf16 v[74:77], v[146:149], v[186:189], v[74:77]
	v_mfma_f32_16x16x32_bf16 v[66:69], v[154:157], v[186:189], v[66:69]
	v_mfma_f32_16x16x32_bf16 v[134:137], v[150:153], v[166:169], v[134:137]
	v_mfma_f32_16x16x32_bf16 v[130:133], v[158:161], v[166:169], v[130:133]
	v_mfma_f32_16x16x32_bf16 v[118:121], v[150:153], v[174:177], v[118:121]
	v_mfma_f32_16x16x32_bf16 v[114:117], v[158:161], v[174:177], v[114:117]
	v_mfma_f32_16x16x32_bf16 v[102:105], v[150:153], v[182:185], v[102:105]
	v_mfma_f32_16x16x32_bf16 v[98:101], v[158:161], v[182:185], v[98:101]
	v_mfma_f32_16x16x32_bf16 v[74:77], v[150:153], v[190:193], v[74:77]
	v_mfma_f32_16x16x32_bf16 v[66:69], v[158:161], v[190:193], v[66:69]
	s_setprio 0
	s_barrier
	s_mov_b32 m0, s67
	v_lshl_add_u64 v[200:201], v[200:201], 0, s[80:81]
	ds_read_b128 v[162:165], v225 offset:49152
	ds_read_b128 v[166:169], v225 offset:50176
	ds_read_b128 v[170:173], v225 offset:51200
	ds_read_b128 v[174:177], v225 offset:52224
	ds_read_b128 v[178:181], v225 offset:53248
	ds_read_b128 v[182:185], v225 offset:54272
	ds_read_b128 v[186:189], v225 offset:55296
	ds_read_b128 v[190:193], v225 offset:56320
	global_load_lds_dwordx4 v[200:201], off
	v_lshl_add_u64 v[200:201], v[210:211], 0, s[80:81]
	s_mov_b32 m0, s68
	s_nop 0
	global_load_lds_dwordx4 v[200:201], off
	v_lshl_add_u64 v[200:201], s[26:27], 0, v[0:1]
	s_mov_b32 m0, s72
	s_nop 0
	global_load_lds_dwordx4 v[200:201], off
	v_lshl_add_u64 v[200:201], s[26:27], 0, v[204:205]
	s_mov_b32 m0, s73
	s_nop 0
	global_load_lds_dwordx4 v[200:201], off
	v_lshl_add_u64 v[200:201], v[212:213], 0, s[80:81]
	s_mov_b32 m0, s69
	s_nop 0
	global_load_lds_dwordx4 v[200:201], off
	v_lshl_add_u64 v[200:201], v[214:215], 0, s[80:81]
	s_mov_b32 m0, s70
	s_nop 0
	global_load_lds_dwordx4 v[200:201], off
	s_waitcnt vmcnt(8)
	s_waitcnt lgkmcnt(0)
	s_barrier
	s_setprio 1
	v_mfma_f32_16x16x32_bf16 v[62:65], v[70:73], v[162:165], v[62:65]
	v_mfma_f32_16x16x32_bf16 v[58:61], v[82:85], v[162:165], v[58:61]
	v_mfma_f32_16x16x32_bf16 v[46:49], v[70:73], v[170:173], v[46:49]
	v_mfma_f32_16x16x32_bf16 v[42:45], v[82:85], v[170:173], v[42:45]
	v_mfma_f32_16x16x32_bf16 v[30:33], v[70:73], v[178:181], v[30:33]
	v_mfma_f32_16x16x32_bf16 v[26:29], v[82:85], v[178:181], v[26:29]
	v_mfma_f32_16x16x32_bf16 v[14:17], v[70:73], v[186:189], v[14:17]
	v_mfma_f32_16x16x32_bf16 v[10:13], v[82:85], v[186:189], v[10:13]
	v_mfma_f32_16x16x32_bf16 v[62:65], v[78:81], v[166:169], v[62:65]
	v_mfma_f32_16x16x32_bf16 v[58:61], v[86:89], v[166:169], v[58:61]
	v_mfma_f32_16x16x32_bf16 v[46:49], v[78:81], v[174:177], v[46:49]
	v_mfma_f32_16x16x32_bf16 v[42:45], v[86:89], v[174:177], v[42:45]
	v_mfma_f32_16x16x32_bf16 v[30:33], v[78:81], v[182:185], v[30:33]
	v_mfma_f32_16x16x32_bf16 v[26:29], v[86:89], v[182:185], v[26:29]
	v_mfma_f32_16x16x32_bf16 v[14:17], v[78:81], v[190:193], v[14:17]
	v_mfma_f32_16x16x32_bf16 v[10:13], v[86:89], v[190:193], v[10:13]
	v_mfma_f32_16x16x32_bf16 v[54:57], v[146:149], v[162:165], v[54:57]
	v_mfma_f32_16x16x32_bf16 v[50:53], v[154:157], v[162:165], v[50:53]
	v_mfma_f32_16x16x32_bf16 v[38:41], v[146:149], v[170:173], v[38:41]
	v_mfma_f32_16x16x32_bf16 v[34:37], v[154:157], v[170:173], v[34:37]
	v_mfma_f32_16x16x32_bf16 v[22:25], v[146:149], v[178:181], v[22:25]
	v_mfma_f32_16x16x32_bf16 v[18:21], v[154:157], v[178:181], v[18:21]
	v_mfma_f32_16x16x32_bf16 v[6:9], v[146:149], v[186:189], v[6:9]
	v_mfma_f32_16x16x32_bf16 v[2:5], v[154:157], v[186:189], v[2:5]
	v_mfma_f32_16x16x32_bf16 v[54:57], v[150:153], v[166:169], v[54:57]
	v_mfma_f32_16x16x32_bf16 v[50:53], v[158:161], v[166:169], v[50:53]
	v_mfma_f32_16x16x32_bf16 v[38:41], v[150:153], v[174:177], v[38:41]
	v_mfma_f32_16x16x32_bf16 v[34:37], v[158:161], v[174:177], v[34:37]
	v_mfma_f32_16x16x32_bf16 v[22:25], v[150:153], v[182:185], v[22:25]
	v_mfma_f32_16x16x32_bf16 v[18:21], v[158:161], v[182:185], v[18:21]
	v_mfma_f32_16x16x32_bf16 v[6:9], v[150:153], v[190:193], v[6:9]
	v_mfma_f32_16x16x32_bf16 v[2:5], v[158:161], v[190:193], v[2:5]
	s_setprio 0
	s_barrier
	s_movk_i32 s17, 0x100
	s_andn2_b64 vcc, exec, s[24:25]
	s_mov_b64 s[26:27], -1
	s_mov_b64 s[24:25], 0
	s_cbranch_vccz .LBB0_1010
	s_and_b64 vcc, exec, s[12:13]
	s_cbranch_vccz .LBB0_1013
	s_barrier

.LBB0_1107:
	v_add_u32_e32 v142, s50, v238
	v_add_u32_e32 v158, s53, v238
	ds_read_b128 v[130:133], v142
	ds_read_b128 v[134:137], v142 offset:1024
	ds_read_b128 v[138:141], v142 offset:2048
	ds_read_b128 v[142:145], v142 offset:3072
	ds_read_b128 v[146:149], v158
	ds_read_b128 v[150:153], v158 offset:1024
	ds_read_b128 v[154:157], v158 offset:2048
	ds_read_b128 v[158:161], v158 offset:3072
	s_add_u32 s36, s34, 0xfffc0080
	s_addc_u32 s37, s35, -1
	s_cmp_eq_u32 s74, 12
	s_cselect_b32 s39, s7, s37
	s_cselect_b32 s38, s25, s36
	s_cselect_b32 s37, s23, s73
	s_cselect_b32 s36, s31, s72
	v_lshl_add_u64 v[200:201], s[34:35], 0, v[210:211]
	s_add_i32 m0, s56, 0xc000
	ds_read_b128 v[162:165], v240
	ds_read_b128 v[166:169], v240 offset:1024
	ds_read_b128 v[170:173], v240 offset:2048
	ds_read_b128 v[174:177], v240 offset:3072
	ds_read_b128 v[178:181], v240 offset:4096
	ds_read_b128 v[182:185], v240 offset:5120
	ds_read_b128 v[186:189], v240 offset:6144
	ds_read_b128 v[190:193], v240 offset:7168
	global_load_lds_dwordx4 v[200:201], off
	v_lshl_add_u64 v[200:201], s[34:35], 0, v[212:213]
	s_add_i32 m0, s56, 0xe000
	s_nop 0
	global_load_lds_dwordx4 v[200:201], off
	s_waitcnt vmcnt(8)
	s_waitcnt lgkmcnt(0)
	s_barrier
	s_setprio 1
	v_mfma_f32_16x16x32_bf16 v[126:129], v[130:133], v[162:165], v[126:129]
	v_mfma_f32_16x16x32_bf16 v[122:125], v[138:141], v[162:165], v[122:125]
	v_mfma_f32_16x16x32_bf16 v[110:113], v[130:133], v[170:173], v[110:113]
	v_mfma_f32_16x16x32_bf16 v[106:109], v[138:141], v[170:173], v[106:109]
	v_mfma_f32_16x16x32_bf16 v[94:97], v[130:133], v[178:181], v[94:97]
	v_mfma_f32_16x16x32_bf16 v[90:93], v[138:141], v[178:181], v[90:93]
	v_mfma_f32_16x16x32_bf16 v[78:81], v[130:133], v[186:189], v[78:81]
	v_mfma_f32_16x16x32_bf16 v[74:77], v[138:141], v[186:189], v[74:77]
	v_mfma_f32_16x16x32_bf16 v[126:129], v[134:137], v[166:169], v[126:129]
	v_mfma_f32_16x16x32_bf16 v[122:125], v[142:145], v[166:169], v[122:125]
	v_mfma_f32_16x16x32_bf16 v[110:113], v[134:137], v[174:177], v[110:113]
	v_mfma_f32_16x16x32_bf16 v[106:109], v[142:145], v[174:177], v[106:109]
	v_mfma_f32_16x16x32_bf16 v[94:97], v[134:137], v[182:185], v[94:97]
	v_mfma_f32_16x16x32_bf16 v[90:93], v[142:145], v[182:185], v[90:93]
	v_mfma_f32_16x16x32_bf16 v[78:81], v[134:137], v[190:193], v[78:81]
	v_mfma_f32_16x16x32_bf16 v[74:77], v[142:145], v[190:193], v[74:77]
	v_mfma_f32_16x16x32_bf16 v[118:121], v[146:149], v[162:165], v[118:121]
	v_mfma_f32_16x16x32_bf16 v[114:117], v[154:157], v[162:165], v[114:117]
	v_mfma_f32_16x16x32_bf16 v[102:105], v[146:149], v[170:173], v[102:105]
	v_mfma_f32_16x16x32_bf16 v[98:101], v[154:157], v[170:173], v[98:101]
	v_mfma_f32_16x16x32_bf16 v[86:89], v[146:149], v[178:181], v[86:89]
	v_mfma_f32_16x16x32_bf16 v[82:85], v[154:157], v[178:181], v[82:85]
	v_mfma_f32_16x16x32_bf16 v[70:73], v[146:149], v[186:189], v[70:73]
	v_mfma_f32_16x16x32_bf16 v[66:69], v[154:157], v[186:189], v[66:69]
	v_mfma_f32_16x16x32_bf16 v[118:121], v[150:153], v[166:169], v[118:121]
	v_mfma_f32_16x16x32_bf16 v[114:117], v[158:161], v[166:169], v[114:117]
	v_mfma_f32_16x16x32_bf16 v[102:105], v[150:153], v[174:177], v[102:105]
	v_mfma_f32_16x16x32_bf16 v[98:101], v[158:161], v[174:177], v[98:101]
	v_mfma_f32_16x16x32_bf16 v[86:89], v[150:153], v[182:185], v[86:89]
	v_mfma_f32_16x16x32_bf16 v[82:85], v[158:161], v[182:185], v[82:85]
	v_mfma_f32_16x16x32_bf16 v[70:73], v[150:153], v[190:193], v[70:73]
	v_mfma_f32_16x16x32_bf16 v[66:69], v[158:161], v[190:193], v[66:69]
	s_setprio 0
	s_barrier
	s_mov_b32 m0, s51
	v_lshl_add_u64 v[200:201], s[36:37], 0, v[0:1]
	s_add_u32 s76, s36, 0x40000
	ds_read_b128 v[162:165], v240 offset:16384
	ds_read_b128 v[166:169], v240 offset:17408
	ds_read_b128 v[170:173], v240 offset:18432
	ds_read_b128 v[174:177], v240 offset:19456
	ds_read_b128 v[178:181], v240 offset:20480
	ds_read_b128 v[182:185], v240 offset:21504
	ds_read_b128 v[186:189], v240 offset:22528
	ds_read_b128 v[190:193], v240 offset:23552
	global_load_lds_dwordx4 v[200:201], off
	v_lshl_add_u64 v[214:215], s[36:37], 0, v[208:209]
	s_mov_b32 m0, s52
	s_addc_u32 s77, s37, 0
	global_load_lds_dwordx4 v[214:215], off
	v_lshl_add_u64 v[216:217], s[76:77], 0, v[0:1]
	s_mov_b32 m0, s54
	v_lshl_add_u64 v[218:219], s[38:39], 0, v[206:207]
	global_load_lds_dwordx4 v[216:217], off
	v_lshl_add_u64 v[216:217], s[76:77], 0, v[208:209]
	s_mov_b32 m0, s55
	s_nop 0
	global_load_lds_dwordx4 v[216:217], off
	v_lshl_add_u64 v[216:217], s[38:39], 0, v[204:205]
	s_mov_b32 m0, s56
	s_nop 0
	global_load_lds_dwordx4 v[216:217], off
	s_mov_b32 m0, s57
	s_nop 0
	global_load_lds_dwordx4 v[218:219], off
	s_waitcnt vmcnt(8)
	s_waitcnt lgkmcnt(0)
	s_barrier
	s_setprio 1
	v_mfma_f32_16x16x32_bf16 v[62:65], v[130:133], v[162:165], v[62:65]
	v_mfma_f32_16x16x32_bf16 v[58:61], v[138:141], v[162:165], v[58:61]
	v_mfma_f32_16x16x32_bf16 v[46:49], v[130:133], v[170:173], v[46:49]
	v_mfma_f32_16x16x32_bf16 v[42:45], v[138:141], v[170:173], v[42:45]
	v_mfma_f32_16x16x32_bf16 v[30:33], v[130:133], v[178:181], v[30:33]
	v_mfma_f32_16x16x32_bf16 v[26:29], v[138:141], v[178:181], v[26:29]
	v_mfma_f32_16x16x32_bf16 v[14:17], v[130:133], v[186:189], v[14:17]
	v_mfma_f32_16x16x32_bf16 v[10:13], v[138:141], v[186:189], v[10:13]
	v_mfma_f32_16x16x32_bf16 v[62:65], v[134:137], v[166:169], v[62:65]
	v_mfma_f32_16x16x32_bf16 v[58:61], v[142:145], v[166:169], v[58:61]
	v_mfma_f32_16x16x32_bf16 v[46:49], v[134:137], v[174:177], v[46:49]
	v_mfma_f32_16x16x32_bf16 v[42:45], v[142:145], v[174:177], v[42:45]
	v_mfma_f32_16x16x32_bf16 v[30:33], v[134:137], v[182:185], v[30:33]
	v_mfma_f32_16x16x32_bf16 v[26:29], v[142:145], v[182:185], v[26:29]
	v_mfma_f32_16x16x32_bf16 v[14:17], v[134:137], v[190:193], v[14:17]
	v_mfma_f32_16x16x32_bf16 v[10:13], v[142:145], v[190:193], v[10:13]
	v_mfma_f32_16x16x32_bf16 v[54:57], v[146:149], v[162:165], v[54:57]
	v_mfma_f32_16x16x32_bf16 v[50:53], v[154:157], v[162:165], v[50:53]
	v_mfma_f32_16x16x32_bf16 v[38:41], v[146:149], v[170:173], v[38:41]
	v_mfma_f32_16x16x32_bf16 v[34:37], v[154:157], v[170:173], v[34:37]
	v_mfma_f32_16x16x32_bf16 v[22:25], v[146:149], v[178:181], v[22:25]
	v_mfma_f32_16x16x32_bf16 v[18:21], v[154:157], v[178:181], v[18:21]
	v_mfma_f32_16x16x32_bf16 v[6:9], v[146:149], v[186:189], v[6:9]
	v_mfma_f32_16x16x32_bf16 v[2:5], v[154:157], v[186:189], v[2:5]
	v_mfma_f32_16x16x32_bf16 v[54:57], v[150:153], v[166:169], v[54:57]
	v_mfma_f32_16x16x32_bf16 v[50:53], v[158:161], v[166:169], v[50:53]
	v_mfma_f32_16x16x32_bf16 v[38:41], v[150:153], v[174:177], v[38:41]
	v_mfma_f32_16x16x32_bf16 v[34:37], v[158:161], v[174:177], v[34:37]
	v_mfma_f32_16x16x32_bf16 v[22:25], v[150:153], v[182:185], v[22:25]
	v_mfma_f32_16x16x32_bf16 v[18:21], v[158:161], v[182:185], v[18:21]
	v_mfma_f32_16x16x32_bf16 v[6:9], v[150:153], v[190:193], v[6:9]
	v_mfma_f32_16x16x32_bf16 v[2:5], v[158:161], v[190:193], v[2:5]
	s_setprio 0
	s_barrier
	v_add_u32_e32 v142, s62, v238
	v_add_u32_e32 v158, s67, v238
	ds_read_b128 v[130:133], v142
	ds_read_b128 v[134:137], v142 offset:1024
	ds_read_b128 v[138:141], v142 offset:2048
	ds_read_b128 v[142:145], v142 offset:3072
	ds_read_b128 v[146:149], v158
	ds_read_b128 v[150:153], v158 offset:1024
	ds_read_b128 v[154:157], v158 offset:2048
	ds_read_b128 v[158:161], v158 offset:3072
	s_add_u32 s38, s38, 0x40000
	s_addc_u32 s39, s39, 0
	s_mov_b32 m0, s58
	v_lshl_add_u64 v[220:221], s[38:39], 0, v[204:205]
	ds_read_b128 v[162:165], v240 offset:32768
	ds_read_b128 v[166:169], v240 offset:33792
	ds_read_b128 v[170:173], v240 offset:34816
	ds_read_b128 v[174:177], v240 offset:35840
	ds_read_b128 v[178:181], v240 offset:36864
	ds_read_b128 v[182:185], v240 offset:37888
	ds_read_b128 v[186:189], v240 offset:38912
	ds_read_b128 v[190:193], v240 offset:39936
	global_load_lds_dwordx4 v[220:221], off
	v_lshl_add_u64 v[220:221], s[38:39], 0, v[206:207]
	s_mov_b32 m0, s59
	s_nop 0
	global_load_lds_dwordx4 v[220:221], off
	s_waitcnt vmcnt(8)
	s_waitcnt lgkmcnt(0)
	s_barrier
	s_setprio 1
	v_mfma_f32_16x16x32_bf16 v[126:129], v[130:133], v[162:165], v[126:129]
	v_mfma_f32_16x16x32_bf16 v[122:125], v[138:141], v[162:165], v[122:125]
	v_mfma_f32_16x16x32_bf16 v[110:113], v[130:133], v[170:173], v[110:113]
	v_mfma_f32_16x16x32_bf16 v[106:109], v[138:141], v[170:173], v[106:109]
	v_mfma_f32_16x16x32_bf16 v[94:97], v[130:133], v[178:181], v[94:97]
	v_mfma_f32_16x16x32_bf16 v[90:93], v[138:141], v[178:181], v[90:93]
	v_mfma_f32_16x16x32_bf16 v[78:81], v[130:133], v[186:189], v[78:81]
	v_mfma_f32_16x16x32_bf16 v[74:77], v[138:141], v[186:189], v[74:77]
	v_mfma_f32_16x16x32_bf16 v[126:129], v[134:137], v[166:169], v[126:129]
	v_mfma_f32_16x16x32_bf16 v[122:125], v[142:145], v[166:169], v[122:125]
	v_mfma_f32_16x16x32_bf16 v[110:113], v[134:137], v[174:177], v[110:113]
	v_mfma_f32_16x16x32_bf16 v[106:109], v[142:145], v[174:177], v[106:109]
	v_mfma_f32_16x16x32_bf16 v[94:97], v[134:137], v[182:185], v[94:97]
	v_mfma_f32_16x16x32_bf16 v[90:93], v[142:145], v[182:185], v[90:93]
	v_mfma_f32_16x16x32_bf16 v[78:81], v[134:137], v[190:193], v[78:81]
	v_mfma_f32_16x16x32_bf16 v[74:77], v[142:145], v[190:193], v[74:77]
	v_mfma_f32_16x16x32_bf16 v[118:121], v[146:149], v[162:165], v[118:121]
	v_mfma_f32_16x16x32_bf16 v[114:117], v[154:157], v[162:165], v[114:117]
	v_mfma_f32_16x16x32_bf16 v[102:105], v[146:149], v[170:173], v[102:105]
	v_mfma_f32_16x16x32_bf16 v[98:101], v[154:157], v[170:173], v[98:101]
	v_mfma_f32_16x16x32_bf16 v[86:89], v[146:149], v[178:181], v[86:89]
	v_mfma_f32_16x16x32_bf16 v[82:85], v[154:157], v[178:181], v[82:85]
	v_mfma_f32_16x16x32_bf16 v[70:73], v[146:149], v[186:189], v[70:73]
	v_mfma_f32_16x16x32_bf16 v[66:69], v[154:157], v[186:189], v[66:69]
	v_mfma_f32_16x16x32_bf16 v[118:121], v[150:153], v[166:169], v[118:121]
	v_mfma_f32_16x16x32_bf16 v[114:117], v[158:161], v[166:169], v[114:117]
	v_mfma_f32_16x16x32_bf16 v[102:105], v[150:153], v[174:177], v[102:105]
	v_mfma_f32_16x16x32_bf16 v[98:101], v[158:161], v[174:177], v[98:101]
	v_mfma_f32_16x16x32_bf16 v[86:89], v[150:153], v[182:185], v[86:89]
	v_mfma_f32_16x16x32_bf16 v[82:85], v[158:161], v[182:185], v[82:85]
	v_mfma_f32_16x16x32_bf16 v[70:73], v[150:153], v[190:193], v[70:73]
	v_mfma_f32_16x16x32_bf16 v[66:69], v[158:161], v[190:193], v[66:69]
	s_setprio 0
	s_barrier
	s_mov_b32 m0, s63
	v_lshl_add_u64 v[200:201], v[200:201], 0, s[80:81]
	s_add_u32 s36, s36, 0x40080
	ds_read_b128 v[162:165], v240 offset:49152
	ds_read_b128 v[166:169], v240 offset:50176
	ds_read_b128 v[170:173], v240 offset:51200
	ds_read_b128 v[174:177], v240 offset:52224
	ds_read_b128 v[178:181], v240 offset:53248
	ds_read_b128 v[182:185], v240 offset:54272
	ds_read_b128 v[186:189], v240 offset:55296
	ds_read_b128 v[190:193], v240 offset:56320
	global_load_lds_dwordx4 v[200:201], off
	v_lshl_add_u64 v[200:201], v[214:215], 0, s[80:81]
	s_mov_b32 m0, s64
	s_addc_u32 s37, s37, 0
	global_load_lds_dwordx4 v[200:201], off
	v_lshl_add_u64 v[200:201], s[36:37], 0, v[0:1]
	s_mov_b32 m0, s68
	s_nop 0
	global_load_lds_dwordx4 v[200:201], off
	v_lshl_add_u64 v[200:201], s[36:37], 0, v[208:209]
	s_mov_b32 m0, s69
	s_nop 0
	global_load_lds_dwordx4 v[200:201], off
	v_lshl_add_u64 v[200:201], v[216:217], 0, s[80:81]
	s_mov_b32 m0, s65
	s_nop 0
	global_load_lds_dwordx4 v[200:201], off
	v_lshl_add_u64 v[200:201], v[218:219], 0, s[80:81]
	s_mov_b32 m0, s66
	s_nop 0
	global_load_lds_dwordx4 v[200:201], off
	s_waitcnt vmcnt(8)
	s_waitcnt lgkmcnt(0)
	s_barrier
	s_setprio 1
	v_mfma_f32_16x16x32_bf16 v[62:65], v[130:133], v[162:165], v[62:65]
	v_mfma_f32_16x16x32_bf16 v[58:61], v[138:141], v[162:165], v[58:61]
	v_mfma_f32_16x16x32_bf16 v[46:49], v[130:133], v[170:173], v[46:49]
	v_mfma_f32_16x16x32_bf16 v[42:45], v[138:141], v[170:173], v[42:45]
	v_mfma_f32_16x16x32_bf16 v[30:33], v[130:133], v[178:181], v[30:33]
	v_mfma_f32_16x16x32_bf16 v[26:29], v[138:141], v[178:181], v[26:29]
	v_mfma_f32_16x16x32_bf16 v[14:17], v[130:133], v[186:189], v[14:17]
	v_mfma_f32_16x16x32_bf16 v[10:13], v[138:141], v[186:189], v[10:13]
	v_mfma_f32_16x16x32_bf16 v[62:65], v[134:137], v[166:169], v[62:65]
	v_mfma_f32_16x16x32_bf16 v[58:61], v[142:145], v[166:169], v[58:61]
	v_mfma_f32_16x16x32_bf16 v[46:49], v[134:137], v[174:177], v[46:49]
	v_mfma_f32_16x16x32_bf16 v[42:45], v[142:145], v[174:177], v[42:45]
	v_mfma_f32_16x16x32_bf16 v[30:33], v[134:137], v[182:185], v[30:33]
	v_mfma_f32_16x16x32_bf16 v[26:29], v[142:145], v[182:185], v[26:29]
	v_mfma_f32_16x16x32_bf16 v[14:17], v[134:137], v[190:193], v[14:17]
	v_mfma_f32_16x16x32_bf16 v[10:13], v[142:145], v[190:193], v[10:13]
	v_mfma_f32_16x16x32_bf16 v[54:57], v[146:149], v[162:165], v[54:57]
	v_mfma_f32_16x16x32_bf16 v[50:53], v[154:157], v[162:165], v[50:53]
	v_mfma_f32_16x16x32_bf16 v[38:41], v[146:149], v[170:173], v[38:41]
	v_mfma_f32_16x16x32_bf16 v[34:37], v[154:157], v[170:173], v[34:37]
	v_mfma_f32_16x16x32_bf16 v[22:25], v[146:149], v[178:181], v[22:25]
	v_mfma_f32_16x16x32_bf16 v[18:21], v[154:157], v[178:181], v[18:21]
	v_mfma_f32_16x16x32_bf16 v[6:9], v[146:149], v[186:189], v[6:9]
	v_mfma_f32_16x16x32_bf16 v[2:5], v[154:157], v[186:189], v[2:5]
	v_mfma_f32_16x16x32_bf16 v[54:57], v[150:153], v[166:169], v[54:57]
	v_mfma_f32_16x16x32_bf16 v[50:53], v[158:161], v[166:169], v[50:53]
	v_mfma_f32_16x16x32_bf16 v[38:41], v[150:153], v[174:177], v[38:41]
	v_mfma_f32_16x16x32_bf16 v[34:37], v[158:161], v[174:177], v[34:37]
	v_mfma_f32_16x16x32_bf16 v[22:25], v[150:153], v[182:185], v[22:25]
	v_mfma_f32_16x16x32_bf16 v[18:21], v[158:161], v[182:185], v[18:21]
	v_mfma_f32_16x16x32_bf16 v[6:9], v[150:153], v[190:193], v[6:9]
	v_mfma_f32_16x16x32_bf16 v[2:5], v[158:161], v[190:193], v[2:5]
	s_setprio 0
	s_barrier
	s_add_i32 s74, s74, 2
	s_add_u32 s34, s34, 0x100
	s_addc_u32 s35, s35, 0
	s_add_u32 s72, s72, 0x100
	s_addc_u32 s73, s73, 0
	s_cmp_gt_u32 s74, 13
	s_cbranch_scc0 .LBB0_1107
	s_and_b64 vcc, exec, s[18:19]
	s_cbranch_vccz .LBB0_1110
	s_barrier

.LBB0_1223:
	v_add_u32_e32 v156, s46, v160
	ds_read_b128 v[166:169], v156
	ds_read_b128 v[170:173], v156 offset:1024
	ds_read_b128 v[174:177], v156 offset:2048
	ds_read_b128 v[178:181], v156 offset:3072
	v_add_u32_e32 v156, s49, v160
	ds_read_b128 v[182:185], v156
	ds_read_b128 v[186:189], v156 offset:1024
	ds_read_b128 v[190:193], v156 offset:2048
	ds_read_b128 v[204:207], v156 offset:3072
	s_add_u32 s30, s28, 0xfffc0080
	s_addc_u32 s31, s29, -1
	s_cmp_eq_u32 s71, 12
	s_cselect_b32 s35, s21, s31
	s_cselect_b32 s34, s67, s30
	s_cselect_b32 s31, s19, s70
	s_cselect_b32 s30, s68, s69
	v_lshl_add_u64 v[156:157], s[28:29], 0, v[152:153]
	s_add_i32 m0, s52, 0xc000
	ds_read_b128 v[208:211], v164
	ds_read_b128 v[212:215], v164 offset:1024
	ds_read_b128 v[216:219], v164 offset:2048
	ds_read_b128 v[220:223], v164 offset:3072
	ds_read_b128 v[224:227], v164 offset:4096
	ds_read_b128 v[228:231], v164 offset:5120
	ds_read_b128 v[238:241], v164 offset:6144
	ds_read_b128 v[242:245], v164 offset:7168
	global_load_lds_dwordx4 v[156:157], off
	v_lshl_add_u64 v[156:157], s[28:29], 0, v[154:155]
	s_add_i32 m0, s52, 0xe000
	s_nop 0
	global_load_lds_dwordx4 v[156:157], off
	s_waitcnt vmcnt(8)
	s_waitcnt lgkmcnt(0)
	s_barrier
	s_setprio 1
	v_mfma_f32_16x16x32_bf16 v[142:145], v[166:169], v[208:211], v[142:145]
	v_mfma_f32_16x16x32_bf16 v[138:141], v[174:177], v[208:211], v[138:141]
	v_mfma_f32_16x16x32_bf16 v[126:129], v[166:169], v[216:219], v[126:129]
	v_mfma_f32_16x16x32_bf16 v[122:125], v[174:177], v[216:219], v[122:125]
	v_mfma_f32_16x16x32_bf16 v[110:113], v[166:169], v[224:227], v[110:113]
	v_mfma_f32_16x16x32_bf16 v[106:109], v[174:177], v[224:227], v[106:109]
	v_mfma_f32_16x16x32_bf16 v[94:97], v[166:169], v[238:241], v[94:97]
	v_mfma_f32_16x16x32_bf16 v[90:93], v[174:177], v[238:241], v[90:93]
	v_mfma_f32_16x16x32_bf16 v[142:145], v[170:173], v[212:215], v[142:145]
	v_mfma_f32_16x16x32_bf16 v[138:141], v[178:181], v[212:215], v[138:141]
	v_mfma_f32_16x16x32_bf16 v[126:129], v[170:173], v[220:223], v[126:129]
	v_mfma_f32_16x16x32_bf16 v[122:125], v[178:181], v[220:223], v[122:125]
	v_mfma_f32_16x16x32_bf16 v[110:113], v[170:173], v[228:231], v[110:113]
	v_mfma_f32_16x16x32_bf16 v[106:109], v[178:181], v[228:231], v[106:109]
	v_mfma_f32_16x16x32_bf16 v[94:97], v[170:173], v[242:245], v[94:97]
	v_mfma_f32_16x16x32_bf16 v[90:93], v[178:181], v[242:245], v[90:93]
	v_mfma_f32_16x16x32_bf16 v[134:137], v[182:185], v[208:211], v[134:137]
	v_mfma_f32_16x16x32_bf16 v[130:133], v[190:193], v[208:211], v[130:133]
	v_mfma_f32_16x16x32_bf16 v[118:121], v[182:185], v[216:219], v[118:121]
	v_mfma_f32_16x16x32_bf16 v[114:117], v[190:193], v[216:219], v[114:117]
	v_mfma_f32_16x16x32_bf16 v[102:105], v[182:185], v[224:227], v[102:105]
	v_mfma_f32_16x16x32_bf16 v[98:101], v[190:193], v[224:227], v[98:101]
	v_mfma_f32_16x16x32_bf16 v[86:89], v[182:185], v[238:241], v[86:89]
	v_mfma_f32_16x16x32_bf16 v[82:85], v[190:193], v[238:241], v[82:85]
	v_mfma_f32_16x16x32_bf16 v[134:137], v[186:189], v[212:215], v[134:137]
	v_mfma_f32_16x16x32_bf16 v[130:133], v[204:207], v[212:215], v[130:133]
	v_mfma_f32_16x16x32_bf16 v[118:121], v[186:189], v[220:223], v[118:121]
	v_mfma_f32_16x16x32_bf16 v[114:117], v[204:207], v[220:223], v[114:117]
	v_mfma_f32_16x16x32_bf16 v[102:105], v[186:189], v[228:231], v[102:105]
	v_mfma_f32_16x16x32_bf16 v[98:101], v[204:207], v[228:231], v[98:101]
	v_mfma_f32_16x16x32_bf16 v[86:89], v[186:189], v[242:245], v[86:89]
	v_mfma_f32_16x16x32_bf16 v[82:85], v[204:207], v[242:245], v[82:85]
	s_setprio 0
	s_barrier
	s_mov_b32 m0, s47
	v_lshl_add_u64 v[156:157], s[30:31], 0, v[0:1]
	s_add_u32 s72, s30, 0x40000
	ds_read_b128 v[208:211], v164 offset:16384
	ds_read_b128 v[212:215], v164 offset:17408
	ds_read_b128 v[216:219], v164 offset:18432
	ds_read_b128 v[220:223], v164 offset:19456
	ds_read_b128 v[224:227], v164 offset:20480
	ds_read_b128 v[228:231], v164 offset:21504
	ds_read_b128 v[238:241], v164 offset:22528
	ds_read_b128 v[242:245], v164 offset:23552
	global_load_lds_dwordx4 v[156:157], off
	v_lshl_add_u64 v[200:201], s[30:31], 0, v[150:151]
	s_mov_b32 m0, s48
	s_addc_u32 s73, s31, 0
	global_load_lds_dwordx4 v[200:201], off
	v_lshl_add_u64 v[232:233], s[72:73], 0, v[0:1]
	s_mov_b32 m0, s50
	v_lshl_add_u64 v[246:247], s[34:35], 0, v[148:149]
	global_load_lds_dwordx4 v[232:233], off
	v_lshl_add_u64 v[232:233], s[72:73], 0, v[150:151]
	s_mov_b32 m0, s51
	s_nop 0
	global_load_lds_dwordx4 v[232:233], off
	v_lshl_add_u64 v[232:233], s[34:35], 0, v[146:147]
	s_mov_b32 m0, s52
	s_nop 0
	global_load_lds_dwordx4 v[232:233], off
	s_mov_b32 m0, s53
	s_nop 0
	global_load_lds_dwordx4 v[246:247], off
	s_waitcnt vmcnt(8)
	s_waitcnt lgkmcnt(0)
	s_barrier
	s_setprio 1
	v_mfma_f32_16x16x32_bf16 v[78:81], v[166:169], v[208:211], v[78:81]
	v_mfma_f32_16x16x32_bf16 v[74:77], v[174:177], v[208:211], v[74:77]
	v_mfma_f32_16x16x32_bf16 v[62:65], v[166:169], v[216:219], v[62:65]
	v_mfma_f32_16x16x32_bf16 v[58:61], v[174:177], v[216:219], v[58:61]
	v_mfma_f32_16x16x32_bf16 v[46:49], v[166:169], v[224:227], v[46:49]
	v_mfma_f32_16x16x32_bf16 v[42:45], v[174:177], v[224:227], v[42:45]
	v_mfma_f32_16x16x32_bf16 v[30:33], v[166:169], v[238:241], v[30:33]
	v_mfma_f32_16x16x32_bf16 v[26:29], v[174:177], v[238:241], v[26:29]
	v_mfma_f32_16x16x32_bf16 v[78:81], v[170:173], v[212:215], v[78:81]
	v_mfma_f32_16x16x32_bf16 v[74:77], v[178:181], v[212:215], v[74:77]
	v_mfma_f32_16x16x32_bf16 v[62:65], v[170:173], v[220:223], v[62:65]
	v_mfma_f32_16x16x32_bf16 v[58:61], v[178:181], v[220:223], v[58:61]
	v_mfma_f32_16x16x32_bf16 v[46:49], v[170:173], v[228:231], v[46:49]
	v_mfma_f32_16x16x32_bf16 v[42:45], v[178:181], v[228:231], v[42:45]
	v_mfma_f32_16x16x32_bf16 v[30:33], v[170:173], v[242:245], v[30:33]
	v_mfma_f32_16x16x32_bf16 v[26:29], v[178:181], v[242:245], v[26:29]
	v_mfma_f32_16x16x32_bf16 v[70:73], v[182:185], v[208:211], v[70:73]
	v_mfma_f32_16x16x32_bf16 v[66:69], v[190:193], v[208:211], v[66:69]
	v_mfma_f32_16x16x32_bf16 v[54:57], v[182:185], v[216:219], v[54:57]
	v_mfma_f32_16x16x32_bf16 v[50:53], v[190:193], v[216:219], v[50:53]
	v_mfma_f32_16x16x32_bf16 v[38:41], v[182:185], v[224:227], v[38:41]
	v_mfma_f32_16x16x32_bf16 v[34:37], v[190:193], v[224:227], v[34:37]
	v_mfma_f32_16x16x32_bf16 v[22:25], v[182:185], v[238:241], v[22:25]
	v_mfma_f32_16x16x32_bf16 v[18:21], v[190:193], v[238:241], v[18:21]
	v_mfma_f32_16x16x32_bf16 v[70:73], v[186:189], v[212:215], v[70:73]
	v_mfma_f32_16x16x32_bf16 v[66:69], v[204:207], v[212:215], v[66:69]
	v_mfma_f32_16x16x32_bf16 v[54:57], v[186:189], v[220:223], v[54:57]
	v_mfma_f32_16x16x32_bf16 v[50:53], v[204:207], v[220:223], v[50:53]
	v_mfma_f32_16x16x32_bf16 v[38:41], v[186:189], v[228:231], v[38:41]
	v_mfma_f32_16x16x32_bf16 v[34:37], v[204:207], v[228:231], v[34:37]
	v_mfma_f32_16x16x32_bf16 v[22:25], v[186:189], v[242:245], v[22:25]
	v_mfma_f32_16x16x32_bf16 v[18:21], v[204:207], v[242:245], v[18:21]
	s_setprio 0
	s_barrier
	v_add_u32_e32 v165, s56, v160
	ds_read_b128 v[166:169], v165
	ds_read_b128 v[170:173], v165 offset:1024
	ds_read_b128 v[174:177], v165 offset:2048
	ds_read_b128 v[178:181], v165 offset:3072
	v_add_u32_e32 v165, s61, v160
	ds_read_b128 v[182:185], v165
	ds_read_b128 v[186:189], v165 offset:1024
	ds_read_b128 v[190:193], v165 offset:2048
	ds_read_b128 v[204:207], v165 offset:3072
	s_add_u32 s34, s34, 0x40000
	s_addc_u32 s35, s35, 0
	s_mov_b32 m0, s54
	v_lshl_add_u64 v[248:249], s[34:35], 0, v[146:147]
	ds_read_b128 v[208:211], v164 offset:32768
	ds_read_b128 v[212:215], v164 offset:33792
	ds_read_b128 v[216:219], v164 offset:34816
	ds_read_b128 v[220:223], v164 offset:35840
	ds_read_b128 v[224:227], v164 offset:36864
	ds_read_b128 v[228:231], v164 offset:37888
	ds_read_b128 v[238:241], v164 offset:38912
	ds_read_b128 v[242:245], v164 offset:39936
	global_load_lds_dwordx4 v[248:249], off
	v_lshl_add_u64 v[248:249], s[34:35], 0, v[148:149]
	s_mov_b32 m0, s55
	s_nop 0
	global_load_lds_dwordx4 v[248:249], off
	s_waitcnt vmcnt(8)
	s_waitcnt lgkmcnt(0)
	s_barrier
	s_setprio 1
	v_mfma_f32_16x16x32_bf16 v[142:145], v[166:169], v[208:211], v[142:145]
	v_mfma_f32_16x16x32_bf16 v[138:141], v[174:177], v[208:211], v[138:141]
	v_mfma_f32_16x16x32_bf16 v[126:129], v[166:169], v[216:219], v[126:129]
	v_mfma_f32_16x16x32_bf16 v[122:125], v[174:177], v[216:219], v[122:125]
	v_mfma_f32_16x16x32_bf16 v[110:113], v[166:169], v[224:227], v[110:113]
	v_mfma_f32_16x16x32_bf16 v[106:109], v[174:177], v[224:227], v[106:109]
	v_mfma_f32_16x16x32_bf16 v[94:97], v[166:169], v[238:241], v[94:97]
	v_mfma_f32_16x16x32_bf16 v[90:93], v[174:177], v[238:241], v[90:93]
	v_mfma_f32_16x16x32_bf16 v[142:145], v[170:173], v[212:215], v[142:145]
	v_mfma_f32_16x16x32_bf16 v[138:141], v[178:181], v[212:215], v[138:141]
	v_mfma_f32_16x16x32_bf16 v[126:129], v[170:173], v[220:223], v[126:129]
	v_mfma_f32_16x16x32_bf16 v[122:125], v[178:181], v[220:223], v[122:125]
	v_mfma_f32_16x16x32_bf16 v[110:113], v[170:173], v[228:231], v[110:113]
	v_mfma_f32_16x16x32_bf16 v[106:109], v[178:181], v[228:231], v[106:109]
	v_mfma_f32_16x16x32_bf16 v[94:97], v[170:173], v[242:245], v[94:97]
	v_mfma_f32_16x16x32_bf16 v[90:93], v[178:181], v[242:245], v[90:93]
	v_mfma_f32_16x16x32_bf16 v[134:137], v[182:185], v[208:211], v[134:137]
	v_mfma_f32_16x16x32_bf16 v[130:133], v[190:193], v[208:211], v[130:133]
	v_mfma_f32_16x16x32_bf16 v[118:121], v[182:185], v[216:219], v[118:121]
	v_mfma_f32_16x16x32_bf16 v[114:117], v[190:193], v[216:219], v[114:117]
	v_mfma_f32_16x16x32_bf16 v[102:105], v[182:185], v[224:227], v[102:105]
	v_mfma_f32_16x16x32_bf16 v[98:101], v[190:193], v[224:227], v[98:101]
	v_mfma_f32_16x16x32_bf16 v[86:89], v[182:185], v[238:241], v[86:89]
	v_mfma_f32_16x16x32_bf16 v[82:85], v[190:193], v[238:241], v[82:85]
	v_mfma_f32_16x16x32_bf16 v[134:137], v[186:189], v[212:215], v[134:137]
	v_mfma_f32_16x16x32_bf16 v[130:133], v[204:207], v[212:215], v[130:133]
	v_mfma_f32_16x16x32_bf16 v[118:121], v[186:189], v[220:223], v[118:121]
	v_mfma_f32_16x16x32_bf16 v[114:117], v[204:207], v[220:223], v[114:117]
	v_mfma_f32_16x16x32_bf16 v[102:105], v[186:189], v[228:231], v[102:105]
	v_mfma_f32_16x16x32_bf16 v[98:101], v[204:207], v[228:231], v[98:101]
	v_mfma_f32_16x16x32_bf16 v[86:89], v[186:189], v[242:245], v[86:89]
	v_mfma_f32_16x16x32_bf16 v[82:85], v[204:207], v[242:245], v[82:85]
	s_setprio 0
	s_barrier
	s_mov_b32 m0, s57
	v_lshl_add_u64 v[156:157], v[156:157], 0, s[80:81]
	s_add_u32 s30, s30, 0x40080
	ds_read_b128 v[208:211], v164 offset:49152
	ds_read_b128 v[212:215], v164 offset:50176
	ds_read_b128 v[216:219], v164 offset:51200
	ds_read_b128 v[220:223], v164 offset:52224
	ds_read_b128 v[224:227], v164 offset:53248
	ds_read_b128 v[228:231], v164 offset:54272
	ds_read_b128 v[238:241], v164 offset:55296
	ds_read_b128 v[242:245], v164 offset:56320
	global_load_lds_dwordx4 v[156:157], off
	v_lshl_add_u64 v[156:157], v[200:201], 0, s[80:81]
	s_mov_b32 m0, s58
	s_addc_u32 s31, s31, 0
	global_load_lds_dwordx4 v[156:157], off
	v_lshl_add_u64 v[156:157], s[30:31], 0, v[0:1]
	s_mov_b32 m0, s62
	s_nop 0
	global_load_lds_dwordx4 v[156:157], off
	v_lshl_add_u64 v[156:157], s[30:31], 0, v[150:151]
	s_mov_b32 m0, s63
	s_nop 0
	global_load_lds_dwordx4 v[156:157], off
	v_lshl_add_u64 v[156:157], v[232:233], 0, s[80:81]
	s_mov_b32 m0, s59
	s_nop 0
	global_load_lds_dwordx4 v[156:157], off
	v_lshl_add_u64 v[156:157], v[246:247], 0, s[80:81]
	s_mov_b32 m0, s60
	s_nop 0
	global_load_lds_dwordx4 v[156:157], off
	s_waitcnt vmcnt(8)
	s_waitcnt lgkmcnt(0)
	s_barrier
	s_setprio 1
	v_mfma_f32_16x16x32_bf16 v[78:81], v[166:169], v[208:211], v[78:81]
	v_mfma_f32_16x16x32_bf16 v[74:77], v[174:177], v[208:211], v[74:77]
	v_mfma_f32_16x16x32_bf16 v[62:65], v[166:169], v[216:219], v[62:65]
	v_mfma_f32_16x16x32_bf16 v[58:61], v[174:177], v[216:219], v[58:61]
	v_mfma_f32_16x16x32_bf16 v[46:49], v[166:169], v[224:227], v[46:49]
	v_mfma_f32_16x16x32_bf16 v[42:45], v[174:177], v[224:227], v[42:45]
	v_mfma_f32_16x16x32_bf16 v[30:33], v[166:169], v[238:241], v[30:33]
	v_mfma_f32_16x16x32_bf16 v[26:29], v[174:177], v[238:241], v[26:29]
	v_mfma_f32_16x16x32_bf16 v[78:81], v[170:173], v[212:215], v[78:81]
	v_mfma_f32_16x16x32_bf16 v[74:77], v[178:181], v[212:215], v[74:77]
	v_mfma_f32_16x16x32_bf16 v[62:65], v[170:173], v[220:223], v[62:65]
	v_mfma_f32_16x16x32_bf16 v[58:61], v[178:181], v[220:223], v[58:61]
	v_mfma_f32_16x16x32_bf16 v[46:49], v[170:173], v[228:231], v[46:49]
	v_mfma_f32_16x16x32_bf16 v[42:45], v[178:181], v[228:231], v[42:45]
	v_mfma_f32_16x16x32_bf16 v[30:33], v[170:173], v[242:245], v[30:33]
	v_mfma_f32_16x16x32_bf16 v[26:29], v[178:181], v[242:245], v[26:29]
	v_mfma_f32_16x16x32_bf16 v[70:73], v[182:185], v[208:211], v[70:73]
	v_mfma_f32_16x16x32_bf16 v[66:69], v[190:193], v[208:211], v[66:69]
	v_mfma_f32_16x16x32_bf16 v[54:57], v[182:185], v[216:219], v[54:57]
	v_mfma_f32_16x16x32_bf16 v[50:53], v[190:193], v[216:219], v[50:53]
	v_mfma_f32_16x16x32_bf16 v[38:41], v[182:185], v[224:227], v[38:41]
	v_mfma_f32_16x16x32_bf16 v[34:37], v[190:193], v[224:227], v[34:37]
	v_mfma_f32_16x16x32_bf16 v[22:25], v[182:185], v[238:241], v[22:25]
	v_mfma_f32_16x16x32_bf16 v[18:21], v[190:193], v[238:241], v[18:21]
	v_mfma_f32_16x16x32_bf16 v[70:73], v[186:189], v[212:215], v[70:73]
	v_mfma_f32_16x16x32_bf16 v[66:69], v[204:207], v[212:215], v[66:69]
	v_mfma_f32_16x16x32_bf16 v[54:57], v[186:189], v[220:223], v[54:57]
	v_mfma_f32_16x16x32_bf16 v[50:53], v[204:207], v[220:223], v[50:53]
	v_mfma_f32_16x16x32_bf16 v[38:41], v[186:189], v[228:231], v[38:41]
	v_mfma_f32_16x16x32_bf16 v[34:37], v[204:207], v[228:231], v[34:37]
	v_mfma_f32_16x16x32_bf16 v[22:25], v[186:189], v[242:245], v[22:25]
	v_mfma_f32_16x16x32_bf16 v[18:21], v[204:207], v[242:245], v[18:21]
	s_setprio 0
	s_barrier
	s_add_i32 s71, s71, 2
	s_add_u32 s28, s28, 0x100
	s_addc_u32 s29, s29, 0
	s_add_u32 s69, s69, 0x100
	s_addc_u32 s70, s70, 0
	s_cmp_gt_u32 s71, 13
	s_cbranch_scc0 .LBB0_1223
	s_and_b64 vcc, exec, s[16:17]
	s_cbranch_vccz .LBB0_1226
	s_barrier

.LBB0_1325:
	v_add_u32_e32 v142, s44, v183
	v_add_u32_e32 v168, s47, v183
	ds_read_b128 v[130:133], v142
	ds_read_b128 v[134:137], v142 offset:1024
	ds_read_b128 v[138:141], v142 offset:2048
	ds_read_b128 v[142:145], v142 offset:3072
	ds_read_b128 v[146:149], v168
	ds_read_b128 v[150:153], v168 offset:1024
	ds_read_b128 v[164:167], v168 offset:2048
	ds_read_b128 v[168:171], v168 offset:3072
	s_add_u32 s28, s26, 0xfff00080
	s_addc_u32 s29, s27, -1
	s_cmp_eq_u32 s68, 60
	s_cselect_b32 s31, s17, s29
	s_cselect_b32 s30, s23, s28
	s_cselect_b32 s29, s15, s67
	s_cselect_b32 s28, s25, s66
	v_lshl_add_u64 v[180:181], s[26:27], 0, v[160:161]
	s_add_i32 m0, s50, 0xc000
	ds_read_b128 v[172:175], v185
	ds_read_b128 v[176:179], v185 offset:1024
	ds_read_b128 v[186:189], v185 offset:2048
	ds_read_b128 v[190:193], v185 offset:3072
	ds_read_b128 v[204:207], v185 offset:4096
	ds_read_b128 v[208:211], v185 offset:5120
	ds_read_b128 v[212:215], v185 offset:6144
	ds_read_b128 v[216:219], v185 offset:7168
	global_load_lds_dwordx4 v[180:181], off
	v_lshl_add_u64 v[180:181], s[26:27], 0, v[162:163]
	s_add_i32 m0, s50, 0xe000
	s_nop 0
	global_load_lds_dwordx4 v[180:181], off
	s_waitcnt vmcnt(8)
	s_waitcnt lgkmcnt(0)
	s_barrier
	s_setprio 1
	v_mfma_f32_16x16x32_bf16 v[126:129], v[130:133], v[172:175], v[126:129]
	v_mfma_f32_16x16x32_bf16 v[122:125], v[138:141], v[172:175], v[122:125]
	v_mfma_f32_16x16x32_bf16 v[110:113], v[130:133], v[186:189], v[110:113]
	v_mfma_f32_16x16x32_bf16 v[106:109], v[138:141], v[186:189], v[106:109]
	v_mfma_f32_16x16x32_bf16 v[94:97], v[130:133], v[204:207], v[94:97]
	v_mfma_f32_16x16x32_bf16 v[90:93], v[138:141], v[204:207], v[90:93]
	v_mfma_f32_16x16x32_bf16 v[78:81], v[130:133], v[212:215], v[78:81]
	v_mfma_f32_16x16x32_bf16 v[74:77], v[138:141], v[212:215], v[74:77]
	v_mfma_f32_16x16x32_bf16 v[126:129], v[134:137], v[176:179], v[126:129]
	v_mfma_f32_16x16x32_bf16 v[122:125], v[142:145], v[176:179], v[122:125]
	v_mfma_f32_16x16x32_bf16 v[110:113], v[134:137], v[190:193], v[110:113]
	v_mfma_f32_16x16x32_bf16 v[106:109], v[142:145], v[190:193], v[106:109]
	v_mfma_f32_16x16x32_bf16 v[94:97], v[134:137], v[208:211], v[94:97]
	v_mfma_f32_16x16x32_bf16 v[90:93], v[142:145], v[208:211], v[90:93]
	v_mfma_f32_16x16x32_bf16 v[78:81], v[134:137], v[216:219], v[78:81]
	v_mfma_f32_16x16x32_bf16 v[74:77], v[142:145], v[216:219], v[74:77]
	v_mfma_f32_16x16x32_bf16 v[118:121], v[146:149], v[172:175], v[118:121]
	v_mfma_f32_16x16x32_bf16 v[114:117], v[164:167], v[172:175], v[114:117]
	v_mfma_f32_16x16x32_bf16 v[102:105], v[146:149], v[186:189], v[102:105]
	v_mfma_f32_16x16x32_bf16 v[98:101], v[164:167], v[186:189], v[98:101]
	v_mfma_f32_16x16x32_bf16 v[86:89], v[146:149], v[204:207], v[86:89]
	v_mfma_f32_16x16x32_bf16 v[82:85], v[164:167], v[204:207], v[82:85]
	v_mfma_f32_16x16x32_bf16 v[70:73], v[146:149], v[212:215], v[70:73]
	v_mfma_f32_16x16x32_bf16 v[66:69], v[164:167], v[212:215], v[66:69]
	v_mfma_f32_16x16x32_bf16 v[118:121], v[150:153], v[176:179], v[118:121]
	v_mfma_f32_16x16x32_bf16 v[114:117], v[168:171], v[176:179], v[114:117]
	v_mfma_f32_16x16x32_bf16 v[102:105], v[150:153], v[190:193], v[102:105]
	v_mfma_f32_16x16x32_bf16 v[98:101], v[168:171], v[190:193], v[98:101]
	v_mfma_f32_16x16x32_bf16 v[86:89], v[150:153], v[208:211], v[86:89]
	v_mfma_f32_16x16x32_bf16 v[82:85], v[168:171], v[208:211], v[82:85]
	v_mfma_f32_16x16x32_bf16 v[70:73], v[150:153], v[216:219], v[70:73]
	v_mfma_f32_16x16x32_bf16 v[66:69], v[168:171], v[216:219], v[66:69]
	s_setprio 0
	s_barrier
	s_mov_b32 m0, s45
	v_lshl_add_u64 v[180:181], s[28:29], 0, v[0:1]
	s_add_u32 s70, s28, 0x100000
	ds_read_b128 v[172:175], v185 offset:16384
	ds_read_b128 v[176:179], v185 offset:17408
	ds_read_b128 v[186:189], v185 offset:18432
	ds_read_b128 v[190:193], v185 offset:19456
	ds_read_b128 v[204:207], v185 offset:20480
	ds_read_b128 v[208:211], v185 offset:21504
	ds_read_b128 v[212:215], v185 offset:22528
	ds_read_b128 v[216:219], v185 offset:23552
	global_load_lds_dwordx4 v[180:181], off
	v_lshl_add_u64 v[200:201], s[28:29], 0, v[158:159]
	s_mov_b32 m0, s46
	s_addc_u32 s71, s29, 0
	global_load_lds_dwordx4 v[200:201], off
	v_lshl_add_u64 v[220:221], s[70:71], 0, v[0:1]
	s_mov_b32 m0, s48
	v_lshl_add_u64 v[222:223], s[30:31], 0, v[156:157]
	global_load_lds_dwordx4 v[220:221], off
	v_lshl_add_u64 v[220:221], s[70:71], 0, v[158:159]
	s_mov_b32 m0, s49
	s_nop 0
	global_load_lds_dwordx4 v[220:221], off
	v_lshl_add_u64 v[220:221], s[30:31], 0, v[154:155]
	s_mov_b32 m0, s50
	s_nop 0
	global_load_lds_dwordx4 v[220:221], off
	s_mov_b32 m0, s51
	s_nop 0
	global_load_lds_dwordx4 v[222:223], off
	s_waitcnt vmcnt(8)
	s_waitcnt lgkmcnt(0)
	s_barrier
	s_setprio 1
	v_mfma_f32_16x16x32_bf16 v[62:65], v[130:133], v[172:175], v[62:65]
	v_mfma_f32_16x16x32_bf16 v[58:61], v[138:141], v[172:175], v[58:61]
	v_mfma_f32_16x16x32_bf16 v[46:49], v[130:133], v[186:189], v[46:49]
	v_mfma_f32_16x16x32_bf16 v[42:45], v[138:141], v[186:189], v[42:45]
	v_mfma_f32_16x16x32_bf16 v[30:33], v[130:133], v[204:207], v[30:33]
	v_mfma_f32_16x16x32_bf16 v[26:29], v[138:141], v[204:207], v[26:29]
	v_mfma_f32_16x16x32_bf16 v[14:17], v[130:133], v[212:215], v[14:17]
	v_mfma_f32_16x16x32_bf16 v[10:13], v[138:141], v[212:215], v[10:13]
	v_mfma_f32_16x16x32_bf16 v[62:65], v[134:137], v[176:179], v[62:65]
	v_mfma_f32_16x16x32_bf16 v[58:61], v[142:145], v[176:179], v[58:61]
	v_mfma_f32_16x16x32_bf16 v[46:49], v[134:137], v[190:193], v[46:49]
	v_mfma_f32_16x16x32_bf16 v[42:45], v[142:145], v[190:193], v[42:45]
	v_mfma_f32_16x16x32_bf16 v[30:33], v[134:137], v[208:211], v[30:33]
	v_mfma_f32_16x16x32_bf16 v[26:29], v[142:145], v[208:211], v[26:29]
	v_mfma_f32_16x16x32_bf16 v[14:17], v[134:137], v[216:219], v[14:17]
	v_mfma_f32_16x16x32_bf16 v[10:13], v[142:145], v[216:219], v[10:13]
	v_mfma_f32_16x16x32_bf16 v[54:57], v[146:149], v[172:175], v[54:57]
	v_mfma_f32_16x16x32_bf16 v[50:53], v[164:167], v[172:175], v[50:53]
	v_mfma_f32_16x16x32_bf16 v[38:41], v[146:149], v[186:189], v[38:41]
	v_mfma_f32_16x16x32_bf16 v[34:37], v[164:167], v[186:189], v[34:37]
	v_mfma_f32_16x16x32_bf16 v[22:25], v[146:149], v[204:207], v[22:25]
	v_mfma_f32_16x16x32_bf16 v[18:21], v[164:167], v[204:207], v[18:21]
	v_mfma_f32_16x16x32_bf16 v[6:9], v[146:149], v[212:215], v[6:9]
	v_mfma_f32_16x16x32_bf16 v[2:5], v[164:167], v[212:215], v[2:5]
	v_mfma_f32_16x16x32_bf16 v[54:57], v[150:153], v[176:179], v[54:57]
	v_mfma_f32_16x16x32_bf16 v[50:53], v[168:171], v[176:179], v[50:53]
	v_mfma_f32_16x16x32_bf16 v[38:41], v[150:153], v[190:193], v[38:41]
	v_mfma_f32_16x16x32_bf16 v[34:37], v[168:171], v[190:193], v[34:37]
	v_mfma_f32_16x16x32_bf16 v[22:25], v[150:153], v[208:211], v[22:25]
	v_mfma_f32_16x16x32_bf16 v[18:21], v[168:171], v[208:211], v[18:21]
	v_mfma_f32_16x16x32_bf16 v[6:9], v[150:153], v[216:219], v[6:9]
	v_mfma_f32_16x16x32_bf16 v[2:5], v[168:171], v[216:219], v[2:5]
	s_setprio 0
	s_barrier
	v_add_u32_e32 v142, s55, v183
	v_add_u32_e32 v168, s60, v183
	ds_read_b128 v[130:133], v142
	ds_read_b128 v[134:137], v142 offset:1024
	ds_read_b128 v[138:141], v142 offset:2048
	ds_read_b128 v[142:145], v142 offset:3072
	ds_read_b128 v[146:149], v168
	ds_read_b128 v[150:153], v168 offset:1024
	ds_read_b128 v[164:167], v168 offset:2048
	ds_read_b128 v[168:171], v168 offset:3072
	s_add_u32 s30, s30, 0x100000
	s_addc_u32 s31, s31, 0
	s_mov_b32 m0, s52
	v_lshl_add_u64 v[224:225], s[30:31], 0, v[154:155]
	ds_read_b128 v[172:175], v185 offset:32768
	ds_read_b128 v[176:179], v185 offset:33792
	ds_read_b128 v[186:189], v185 offset:34816
	ds_read_b128 v[190:193], v185 offset:35840
	ds_read_b128 v[204:207], v185 offset:36864
	ds_read_b128 v[208:211], v185 offset:37888
	ds_read_b128 v[212:215], v185 offset:38912
	ds_read_b128 v[216:219], v185 offset:39936
	global_load_lds_dwordx4 v[224:225], off
	v_lshl_add_u64 v[224:225], s[30:31], 0, v[156:157]
	s_mov_b32 m0, s53
	s_nop 0
	global_load_lds_dwordx4 v[224:225], off
	s_waitcnt vmcnt(8)
	s_waitcnt lgkmcnt(0)
	s_barrier
	s_setprio 1
	v_mfma_f32_16x16x32_bf16 v[126:129], v[130:133], v[172:175], v[126:129]
	v_mfma_f32_16x16x32_bf16 v[122:125], v[138:141], v[172:175], v[122:125]
	v_mfma_f32_16x16x32_bf16 v[110:113], v[130:133], v[186:189], v[110:113]
	v_mfma_f32_16x16x32_bf16 v[106:109], v[138:141], v[186:189], v[106:109]
	v_mfma_f32_16x16x32_bf16 v[94:97], v[130:133], v[204:207], v[94:97]
	v_mfma_f32_16x16x32_bf16 v[90:93], v[138:141], v[204:207], v[90:93]
	v_mfma_f32_16x16x32_bf16 v[78:81], v[130:133], v[212:215], v[78:81]
	v_mfma_f32_16x16x32_bf16 v[74:77], v[138:141], v[212:215], v[74:77]
	v_mfma_f32_16x16x32_bf16 v[126:129], v[134:137], v[176:179], v[126:129]
	v_mfma_f32_16x16x32_bf16 v[122:125], v[142:145], v[176:179], v[122:125]
	v_mfma_f32_16x16x32_bf16 v[110:113], v[134:137], v[190:193], v[110:113]
	v_mfma_f32_16x16x32_bf16 v[106:109], v[142:145], v[190:193], v[106:109]
	v_mfma_f32_16x16x32_bf16 v[94:97], v[134:137], v[208:211], v[94:97]
	v_mfma_f32_16x16x32_bf16 v[90:93], v[142:145], v[208:211], v[90:93]
	v_mfma_f32_16x16x32_bf16 v[78:81], v[134:137], v[216:219], v[78:81]
	v_mfma_f32_16x16x32_bf16 v[74:77], v[142:145], v[216:219], v[74:77]
	v_mfma_f32_16x16x32_bf16 v[118:121], v[146:149], v[172:175], v[118:121]
	v_mfma_f32_16x16x32_bf16 v[114:117], v[164:167], v[172:175], v[114:117]
	v_mfma_f32_16x16x32_bf16 v[102:105], v[146:149], v[186:189], v[102:105]
	v_mfma_f32_16x16x32_bf16 v[98:101], v[164:167], v[186:189], v[98:101]
	v_mfma_f32_16x16x32_bf16 v[86:89], v[146:149], v[204:207], v[86:89]
	v_mfma_f32_16x16x32_bf16 v[82:85], v[164:167], v[204:207], v[82:85]
	v_mfma_f32_16x16x32_bf16 v[70:73], v[146:149], v[212:215], v[70:73]
	v_mfma_f32_16x16x32_bf16 v[66:69], v[164:167], v[212:215], v[66:69]
	v_mfma_f32_16x16x32_bf16 v[118:121], v[150:153], v[176:179], v[118:121]
	v_mfma_f32_16x16x32_bf16 v[114:117], v[168:171], v[176:179], v[114:117]
	v_mfma_f32_16x16x32_bf16 v[102:105], v[150:153], v[190:193], v[102:105]
	v_mfma_f32_16x16x32_bf16 v[98:101], v[168:171], v[190:193], v[98:101]
	v_mfma_f32_16x16x32_bf16 v[86:89], v[150:153], v[208:211], v[86:89]
	v_mfma_f32_16x16x32_bf16 v[82:85], v[168:171], v[208:211], v[82:85]
	v_mfma_f32_16x16x32_bf16 v[70:73], v[150:153], v[216:219], v[70:73]
	v_mfma_f32_16x16x32_bf16 v[66:69], v[168:171], v[216:219], v[66:69]
	s_setprio 0
	s_barrier
	s_mov_b32 m0, s56
	v_lshl_add_u64 v[180:181], v[180:181], 0, s[80:81]
	s_add_u32 s28, s28, 0x100080
	ds_read_b128 v[172:175], v185 offset:49152
	ds_read_b128 v[176:179], v185 offset:50176
	ds_read_b128 v[186:189], v185 offset:51200
	ds_read_b128 v[190:193], v185 offset:52224
	ds_read_b128 v[204:207], v185 offset:53248
	ds_read_b128 v[208:211], v185 offset:54272
	ds_read_b128 v[212:215], v185 offset:55296
	ds_read_b128 v[216:219], v185 offset:56320
	global_load_lds_dwordx4 v[180:181], off
	v_lshl_add_u64 v[180:181], v[200:201], 0, s[80:81]
	s_mov_b32 m0, s57
	s_addc_u32 s29, s29, 0
	global_load_lds_dwordx4 v[180:181], off
	v_lshl_add_u64 v[180:181], s[28:29], 0, v[0:1]
	s_mov_b32 m0, s61
	s_nop 0
	global_load_lds_dwordx4 v[180:181], off
	v_lshl_add_u64 v[180:181], s[28:29], 0, v[158:159]
	s_mov_b32 m0, s62
	s_nop 0
	global_load_lds_dwordx4 v[180:181], off
	v_lshl_add_u64 v[180:181], v[220:221], 0, s[80:81]
	s_mov_b32 m0, s58
	s_nop 0
	global_load_lds_dwordx4 v[180:181], off
	v_lshl_add_u64 v[180:181], v[222:223], 0, s[80:81]
	s_mov_b32 m0, s59
	s_nop 0
	global_load_lds_dwordx4 v[180:181], off
	s_waitcnt vmcnt(8)
	s_waitcnt lgkmcnt(0)
	s_barrier
	s_setprio 1
	v_mfma_f32_16x16x32_bf16 v[62:65], v[130:133], v[172:175], v[62:65]
	v_mfma_f32_16x16x32_bf16 v[58:61], v[138:141], v[172:175], v[58:61]
	v_mfma_f32_16x16x32_bf16 v[46:49], v[130:133], v[186:189], v[46:49]
	v_mfma_f32_16x16x32_bf16 v[42:45], v[138:141], v[186:189], v[42:45]
	v_mfma_f32_16x16x32_bf16 v[30:33], v[130:133], v[204:207], v[30:33]
	v_mfma_f32_16x16x32_bf16 v[26:29], v[138:141], v[204:207], v[26:29]
	v_mfma_f32_16x16x32_bf16 v[14:17], v[130:133], v[212:215], v[14:17]
	v_mfma_f32_16x16x32_bf16 v[10:13], v[138:141], v[212:215], v[10:13]
	v_mfma_f32_16x16x32_bf16 v[62:65], v[134:137], v[176:179], v[62:65]
	v_mfma_f32_16x16x32_bf16 v[58:61], v[142:145], v[176:179], v[58:61]
	v_mfma_f32_16x16x32_bf16 v[46:49], v[134:137], v[190:193], v[46:49]
	v_mfma_f32_16x16x32_bf16 v[42:45], v[142:145], v[190:193], v[42:45]
	v_mfma_f32_16x16x32_bf16 v[30:33], v[134:137], v[208:211], v[30:33]
	v_mfma_f32_16x16x32_bf16 v[26:29], v[142:145], v[208:211], v[26:29]
	v_mfma_f32_16x16x32_bf16 v[14:17], v[134:137], v[216:219], v[14:17]
	v_mfma_f32_16x16x32_bf16 v[10:13], v[142:145], v[216:219], v[10:13]
	v_mfma_f32_16x16x32_bf16 v[54:57], v[146:149], v[172:175], v[54:57]
	v_mfma_f32_16x16x32_bf16 v[50:53], v[164:167], v[172:175], v[50:53]
	v_mfma_f32_16x16x32_bf16 v[38:41], v[146:149], v[186:189], v[38:41]
	v_mfma_f32_16x16x32_bf16 v[34:37], v[164:167], v[186:189], v[34:37]
	v_mfma_f32_16x16x32_bf16 v[22:25], v[146:149], v[204:207], v[22:25]
	v_mfma_f32_16x16x32_bf16 v[18:21], v[164:167], v[204:207], v[18:21]
	v_mfma_f32_16x16x32_bf16 v[6:9], v[146:149], v[212:215], v[6:9]
	v_mfma_f32_16x16x32_bf16 v[2:5], v[164:167], v[212:215], v[2:5]
	v_mfma_f32_16x16x32_bf16 v[54:57], v[150:153], v[176:179], v[54:57]
	v_mfma_f32_16x16x32_bf16 v[50:53], v[168:171], v[176:179], v[50:53]
	v_mfma_f32_16x16x32_bf16 v[38:41], v[150:153], v[190:193], v[38:41]
	v_mfma_f32_16x16x32_bf16 v[34:37], v[168:171], v[190:193], v[34:37]
	v_mfma_f32_16x16x32_bf16 v[22:25], v[150:153], v[208:211], v[22:25]
	v_mfma_f32_16x16x32_bf16 v[18:21], v[168:171], v[208:211], v[18:21]
	v_mfma_f32_16x16x32_bf16 v[6:9], v[150:153], v[216:219], v[6:9]
	v_mfma_f32_16x16x32_bf16 v[2:5], v[168:171], v[216:219], v[2:5]
	s_setprio 0
	s_barrier
	s_add_i32 s68, s68, 2
	s_add_u32 s26, s26, 0x100
	s_addc_u32 s27, s27, 0
	s_add_u32 s66, s66, 0x100
	s_addc_u32 s67, s67, 0
	s_cmp_gt_u32 s68, 61
	s_cbranch_scc0 .LBB0_1325
	s_and_b64 vcc, exec, s[12:13]
	s_cbranch_vccz .LBB0_1328
	s_barrier
